# mods GEMV 32 loads in flight; P5+P6 merged into 5 rounds (P5 round 2 beside early P6 tiles), P6 epilogue with prefetched residual loads
# speedup vs baseline: 1.0077x; 1.0077x over previous
.LBB0_32:
	v_readfirstlane_b32 s56, v6
	v_readfirstlane_b32 s57, v7
	v_lshlrev_b32_e32 v99, 2, v217
	v_mov_b32_e32 v98, s12
	s_movk_i32 s13, 3
	s_nop 4
	global_load_dword v100, v99, s[56:57]
	s_add_u32 s56, s56, 0x6000
	s_addc_u32 s57, s57, 0
	global_load_dword v101, v99, s[56:57]
	s_add_u32 s56, s56, 0x6000
	s_addc_u32 s57, s57, 0
	global_load_dword v102, v99, s[56:57]
	s_add_u32 s56, s56, 0x6000
	s_addc_u32 s57, s57, 0
	global_load_dword v103, v99, s[56:57]
	s_add_u32 s56, s56, 0x6000
	s_addc_u32 s57, s57, 0
	global_load_dword v104, v99, s[56:57]
	s_add_u32 s56, s56, 0x6000
	s_addc_u32 s57, s57, 0
	global_load_dword v105, v99, s[56:57]
	s_add_u32 s56, s56, 0x6000
	s_addc_u32 s57, s57, 0
	global_load_dword v106, v99, s[56:57]
	s_add_u32 s56, s56, 0x6000
	s_addc_u32 s57, s57, 0
	global_load_dword v107, v99, s[56:57]
	s_add_u32 s56, s56, 0x6000
	s_addc_u32 s57, s57, 0
	global_load_dword v108, v99, s[56:57]
	s_add_u32 s56, s56, 0x6000
	s_addc_u32 s57, s57, 0
	global_load_dword v109, v99, s[56:57]
	s_add_u32 s56, s56, 0x6000
	s_addc_u32 s57, s57, 0
	global_load_dword v110, v99, s[56:57]
	s_add_u32 s56, s56, 0x6000
	s_addc_u32 s57, s57, 0
	global_load_dword v111, v99, s[56:57]
	s_add_u32 s56, s56, 0x6000
	s_addc_u32 s57, s57, 0
	global_load_dword v112, v99, s[56:57]
	s_add_u32 s56, s56, 0x6000
	s_addc_u32 s57, s57, 0
	global_load_dword v113, v99, s[56:57]
	s_add_u32 s56, s56, 0x6000
	s_addc_u32 s57, s57, 0
	global_load_dword v114, v99, s[56:57]
	s_add_u32 s56, s56, 0x6000
	s_addc_u32 s57, s57, 0
	global_load_dword v115, v99, s[56:57]
	s_add_u32 s56, s56, 0x6000
	s_addc_u32 s57, s57, 0
.Lmods_loop:
	global_load_dword v116, v99, s[56:57]
	s_add_u32 s56, s56, 0x6000
	s_addc_u32 s57, s57, 0
	global_load_dword v117, v99, s[56:57]
	s_add_u32 s56, s56, 0x6000
	s_addc_u32 s57, s57, 0
	global_load_dword v118, v99, s[56:57]
	s_add_u32 s56, s56, 0x6000
	s_addc_u32 s57, s57, 0
	global_load_dword v119, v99, s[56:57]
	s_add_u32 s56, s56, 0x6000
	s_addc_u32 s57, s57, 0
	global_load_dword v120, v99, s[56:57]
	s_add_u32 s56, s56, 0x6000
	s_addc_u32 s57, s57, 0
	global_load_dword v121, v99, s[56:57]
	s_add_u32 s56, s56, 0x6000
	s_addc_u32 s57, s57, 0
	global_load_dword v122, v99, s[56:57]
	s_add_u32 s56, s56, 0x6000
	s_addc_u32 s57, s57, 0
	global_load_dword v123, v99, s[56:57]
	s_add_u32 s56, s56, 0x6000
	s_addc_u32 s57, s57, 0
	global_load_dword v124, v99, s[56:57]
	s_add_u32 s56, s56, 0x6000
	s_addc_u32 s57, s57, 0
	global_load_dword v125, v99, s[56:57]
	s_add_u32 s56, s56, 0x6000
	s_addc_u32 s57, s57, 0
	global_load_dword v126, v99, s[56:57]
	s_add_u32 s56, s56, 0x6000
	s_addc_u32 s57, s57, 0
	global_load_dword v127, v99, s[56:57]
	s_add_u32 s56, s56, 0x6000
	s_addc_u32 s57, s57, 0
	global_load_dword v128, v99, s[56:57]
	s_add_u32 s56, s56, 0x6000
	s_addc_u32 s57, s57, 0
	global_load_dword v129, v99, s[56:57]
	s_add_u32 s56, s56, 0x6000
	s_addc_u32 s57, s57, 0
	global_load_dword v130, v99, s[56:57]
	s_add_u32 s56, s56, 0x6000
	s_addc_u32 s57, s57, 0
	global_load_dword v131, v99, s[56:57]
	s_add_u32 s56, s56, 0x6000
	s_addc_u32 s57, s57, 0
	s_waitcnt vmcnt(16)
	ds_read_b128 v[52:55], v98
	ds_read_b128 v[24:27], v98 offset:4096
	ds_read_b128 v[28:31], v98 offset:8192
	ds_read_b128 v[32:35], v98 offset:12288
	ds_read_b128 v[36:39], v98 offset:16384
	ds_read_b128 v[40:43], v98 offset:20480
	ds_read_b128 v[44:47], v98 offset:24576
	ds_read_b128 v[48:51], v98 offset:28672
	ds_read_b128 v[56:59], v98 offset:32768
	s_waitcnt lgkmcnt(0)
	v_fmac_f32_e32 v8, v100, v52
	v_fmac_f32_e32 v9, v100, v24
	v_fmac_f32_e32 v10, v100, v28
	v_fmac_f32_e32 v11, v100, v32
	v_fmac_f32_e32 v12, v100, v36
	v_fmac_f32_e32 v13, v100, v40
	v_fmac_f32_e32 v14, v100, v44
	v_fmac_f32_e32 v15, v100, v48
	v_fmac_f32_e32 v0, v100, v56
	v_fmac_f32_e32 v8, v101, v53
	v_fmac_f32_e32 v9, v101, v25
	v_fmac_f32_e32 v10, v101, v29
	v_fmac_f32_e32 v11, v101, v33
	v_fmac_f32_e32 v12, v101, v37
	v_fmac_f32_e32 v13, v101, v41
	v_fmac_f32_e32 v14, v101, v45
	v_fmac_f32_e32 v15, v101, v49
	v_fmac_f32_e32 v0, v101, v57
	v_fmac_f32_e32 v8, v102, v54
	v_fmac_f32_e32 v9, v102, v26
	v_fmac_f32_e32 v10, v102, v30
	v_fmac_f32_e32 v11, v102, v34
	v_fmac_f32_e32 v12, v102, v38
	v_fmac_f32_e32 v13, v102, v42
	v_fmac_f32_e32 v14, v102, v46
	v_fmac_f32_e32 v15, v102, v50
	v_fmac_f32_e32 v0, v102, v58
	v_fmac_f32_e32 v8, v103, v55
	v_fmac_f32_e32 v9, v103, v27
	v_fmac_f32_e32 v10, v103, v31
	v_fmac_f32_e32 v11, v103, v35
	v_fmac_f32_e32 v12, v103, v39
	v_fmac_f32_e32 v13, v103, v43
	v_fmac_f32_e32 v14, v103, v47
	v_fmac_f32_e32 v15, v103, v51
	v_fmac_f32_e32 v0, v103, v59
	ds_read_b128 v[52:55], v98 offset:16
	ds_read_b128 v[24:27], v98 offset:4112
	ds_read_b128 v[28:31], v98 offset:8208
	ds_read_b128 v[32:35], v98 offset:12304
	ds_read_b128 v[36:39], v98 offset:16400
	ds_read_b128 v[40:43], v98 offset:20496
	ds_read_b128 v[44:47], v98 offset:24592
	ds_read_b128 v[48:51], v98 offset:28688
	ds_read_b128 v[56:59], v98 offset:32784
	s_waitcnt lgkmcnt(0)
	v_fmac_f32_e32 v8, v104, v52
	v_fmac_f32_e32 v9, v104, v24
	v_fmac_f32_e32 v10, v104, v28
	v_fmac_f32_e32 v11, v104, v32
	v_fmac_f32_e32 v12, v104, v36
	v_fmac_f32_e32 v13, v104, v40
	v_fmac_f32_e32 v14, v104, v44
	v_fmac_f32_e32 v15, v104, v48
	v_fmac_f32_e32 v0, v104, v56
	v_fmac_f32_e32 v8, v105, v53
	v_fmac_f32_e32 v9, v105, v25
	v_fmac_f32_e32 v10, v105, v29
	v_fmac_f32_e32 v11, v105, v33
	v_fmac_f32_e32 v12, v105, v37
	v_fmac_f32_e32 v13, v105, v41
	v_fmac_f32_e32 v14, v105, v45
	v_fmac_f32_e32 v15, v105, v49
	v_fmac_f32_e32 v0, v105, v57
	v_fmac_f32_e32 v8, v106, v54
	v_fmac_f32_e32 v9, v106, v26
	v_fmac_f32_e32 v10, v106, v30
	v_fmac_f32_e32 v11, v106, v34
	v_fmac_f32_e32 v12, v106, v38
	v_fmac_f32_e32 v13, v106, v42
	v_fmac_f32_e32 v14, v106, v46
	v_fmac_f32_e32 v15, v106, v50
	v_fmac_f32_e32 v0, v106, v58
	v_fmac_f32_e32 v8, v107, v55
	v_fmac_f32_e32 v9, v107, v27
	v_fmac_f32_e32 v10, v107, v31
	v_fmac_f32_e32 v11, v107, v35
	v_fmac_f32_e32 v12, v107, v39
	v_fmac_f32_e32 v13, v107, v43
	v_fmac_f32_e32 v14, v107, v47
	v_fmac_f32_e32 v15, v107, v51
	v_fmac_f32_e32 v0, v107, v59
	ds_read_b128 v[52:55], v98 offset:32
	ds_read_b128 v[24:27], v98 offset:4128
	ds_read_b128 v[28:31], v98 offset:8224
	ds_read_b128 v[32:35], v98 offset:12320
	ds_read_b128 v[36:39], v98 offset:16416
	ds_read_b128 v[40:43], v98 offset:20512
	ds_read_b128 v[44:47], v98 offset:24608
	ds_read_b128 v[48:51], v98 offset:28704
	ds_read_b128 v[56:59], v98 offset:32800
	s_waitcnt lgkmcnt(0)
	v_fmac_f32_e32 v8, v108, v52
	v_fmac_f32_e32 v9, v108, v24
	v_fmac_f32_e32 v10, v108, v28
	v_fmac_f32_e32 v11, v108, v32
	v_fmac_f32_e32 v12, v108, v36
	v_fmac_f32_e32 v13, v108, v40
	v_fmac_f32_e32 v14, v108, v44
	v_fmac_f32_e32 v15, v108, v48
	v_fmac_f32_e32 v0, v108, v56
	v_fmac_f32_e32 v8, v109, v53
	v_fmac_f32_e32 v9, v109, v25
	v_fmac_f32_e32 v10, v109, v29
	v_fmac_f32_e32 v11, v109, v33
	v_fmac_f32_e32 v12, v109, v37
	v_fmac_f32_e32 v13, v109, v41
	v_fmac_f32_e32 v14, v109, v45
	v_fmac_f32_e32 v15, v109, v49
	v_fmac_f32_e32 v0, v109, v57
	v_fmac_f32_e32 v8, v110, v54
	v_fmac_f32_e32 v9, v110, v26
	v_fmac_f32_e32 v10, v110, v30
	v_fmac_f32_e32 v11, v110, v34
	v_fmac_f32_e32 v12, v110, v38
	v_fmac_f32_e32 v13, v110, v42
	v_fmac_f32_e32 v14, v110, v46
	v_fmac_f32_e32 v15, v110, v50
	v_fmac_f32_e32 v0, v110, v58
	v_fmac_f32_e32 v8, v111, v55
	v_fmac_f32_e32 v9, v111, v27
	v_fmac_f32_e32 v10, v111, v31
	v_fmac_f32_e32 v11, v111, v35
	v_fmac_f32_e32 v12, v111, v39
	v_fmac_f32_e32 v13, v111, v43
	v_fmac_f32_e32 v14, v111, v47
	v_fmac_f32_e32 v15, v111, v51
	v_fmac_f32_e32 v0, v111, v59
	ds_read_b128 v[52:55], v98 offset:48
	ds_read_b128 v[24:27], v98 offset:4144
	ds_read_b128 v[28:31], v98 offset:8240
	ds_read_b128 v[32:35], v98 offset:12336
	ds_read_b128 v[36:39], v98 offset:16432
	ds_read_b128 v[40:43], v98 offset:20528
	ds_read_b128 v[44:47], v98 offset:24624
	ds_read_b128 v[48:51], v98 offset:28720
	ds_read_b128 v[56:59], v98 offset:32816
	s_waitcnt lgkmcnt(0)
	v_fmac_f32_e32 v8, v112, v52
	v_fmac_f32_e32 v9, v112, v24
	v_fmac_f32_e32 v10, v112, v28
	v_fmac_f32_e32 v11, v112, v32
	v_fmac_f32_e32 v12, v112, v36
	v_fmac_f32_e32 v13, v112, v40
	v_fmac_f32_e32 v14, v112, v44
	v_fmac_f32_e32 v15, v112, v48
	v_fmac_f32_e32 v0, v112, v56
	v_fmac_f32_e32 v8, v113, v53
	v_fmac_f32_e32 v9, v113, v25
	v_fmac_f32_e32 v10, v113, v29
	v_fmac_f32_e32 v11, v113, v33
	v_fmac_f32_e32 v12, v113, v37
	v_fmac_f32_e32 v13, v113, v41
	v_fmac_f32_e32 v14, v113, v45
	v_fmac_f32_e32 v15, v113, v49
	v_fmac_f32_e32 v0, v113, v57
	v_fmac_f32_e32 v8, v114, v54
	v_fmac_f32_e32 v9, v114, v26
	v_fmac_f32_e32 v10, v114, v30
	v_fmac_f32_e32 v11, v114, v34
	v_fmac_f32_e32 v12, v114, v38
	v_fmac_f32_e32 v13, v114, v42
	v_fmac_f32_e32 v14, v114, v46
	v_fmac_f32_e32 v15, v114, v50
	v_fmac_f32_e32 v0, v114, v58
	v_fmac_f32_e32 v8, v115, v55
	v_fmac_f32_e32 v9, v115, v27
	v_fmac_f32_e32 v10, v115, v31
	v_fmac_f32_e32 v11, v115, v35
	v_fmac_f32_e32 v12, v115, v39
	v_fmac_f32_e32 v13, v115, v43
	v_fmac_f32_e32 v14, v115, v47
	v_fmac_f32_e32 v15, v115, v51
	v_fmac_f32_e32 v0, v115, v59
	v_add_u32_e32 v98, 64, v98
	global_load_dword v100, v99, s[56:57]
	s_add_u32 s56, s56, 0x6000
	s_addc_u32 s57, s57, 0
	global_load_dword v101, v99, s[56:57]
	s_add_u32 s56, s56, 0x6000
	s_addc_u32 s57, s57, 0
	global_load_dword v102, v99, s[56:57]
	s_add_u32 s56, s56, 0x6000
	s_addc_u32 s57, s57, 0
	global_load_dword v103, v99, s[56:57]
	s_add_u32 s56, s56, 0x6000
	s_addc_u32 s57, s57, 0
	global_load_dword v104, v99, s[56:57]
	s_add_u32 s56, s56, 0x6000
	s_addc_u32 s57, s57, 0
	global_load_dword v105, v99, s[56:57]
	s_add_u32 s56, s56, 0x6000
	s_addc_u32 s57, s57, 0
	global_load_dword v106, v99, s[56:57]
	s_add_u32 s56, s56, 0x6000
	s_addc_u32 s57, s57, 0
	global_load_dword v107, v99, s[56:57]
	s_add_u32 s56, s56, 0x6000
	s_addc_u32 s57, s57, 0
	global_load_dword v108, v99, s[56:57]
	s_add_u32 s56, s56, 0x6000
	s_addc_u32 s57, s57, 0
	global_load_dword v109, v99, s[56:57]
	s_add_u32 s56, s56, 0x6000
	s_addc_u32 s57, s57, 0
	global_load_dword v110, v99, s[56:57]
	s_add_u32 s56, s56, 0x6000
	s_addc_u32 s57, s57, 0
	global_load_dword v111, v99, s[56:57]
	s_add_u32 s56, s56, 0x6000
	s_addc_u32 s57, s57, 0
	global_load_dword v112, v99, s[56:57]
	s_add_u32 s56, s56, 0x6000
	s_addc_u32 s57, s57, 0
	global_load_dword v113, v99, s[56:57]
	s_add_u32 s56, s56, 0x6000
	s_addc_u32 s57, s57, 0
	global_load_dword v114, v99, s[56:57]
	s_add_u32 s56, s56, 0x6000
	s_addc_u32 s57, s57, 0
	global_load_dword v115, v99, s[56:57]
	s_add_u32 s56, s56, 0x6000
	s_addc_u32 s57, s57, 0
	s_waitcnt vmcnt(16)
	ds_read_b128 v[52:55], v98
	ds_read_b128 v[24:27], v98 offset:4096
	ds_read_b128 v[28:31], v98 offset:8192
	ds_read_b128 v[32:35], v98 offset:12288
	ds_read_b128 v[36:39], v98 offset:16384
	ds_read_b128 v[40:43], v98 offset:20480
	ds_read_b128 v[44:47], v98 offset:24576
	ds_read_b128 v[48:51], v98 offset:28672
	ds_read_b128 v[56:59], v98 offset:32768
	s_waitcnt lgkmcnt(0)
	v_fmac_f32_e32 v8, v116, v52
	v_fmac_f32_e32 v9, v116, v24
	v_fmac_f32_e32 v10, v116, v28
	v_fmac_f32_e32 v11, v116, v32
	v_fmac_f32_e32 v12, v116, v36
	v_fmac_f32_e32 v13, v116, v40
	v_fmac_f32_e32 v14, v116, v44
	v_fmac_f32_e32 v15, v116, v48
	v_fmac_f32_e32 v0, v116, v56
	v_fmac_f32_e32 v8, v117, v53
	v_fmac_f32_e32 v9, v117, v25
	v_fmac_f32_e32 v10, v117, v29
	v_fmac_f32_e32 v11, v117, v33
	v_fmac_f32_e32 v12, v117, v37
	v_fmac_f32_e32 v13, v117, v41
	v_fmac_f32_e32 v14, v117, v45
	v_fmac_f32_e32 v15, v117, v49
	v_fmac_f32_e32 v0, v117, v57
	v_fmac_f32_e32 v8, v118, v54
	v_fmac_f32_e32 v9, v118, v26
	v_fmac_f32_e32 v10, v118, v30
	v_fmac_f32_e32 v11, v118, v34
	v_fmac_f32_e32 v12, v118, v38
	v_fmac_f32_e32 v13, v118, v42
	v_fmac_f32_e32 v14, v118, v46
	v_fmac_f32_e32 v15, v118, v50
	v_fmac_f32_e32 v0, v118, v58
	v_fmac_f32_e32 v8, v119, v55
	v_fmac_f32_e32 v9, v119, v27
	v_fmac_f32_e32 v10, v119, v31
	v_fmac_f32_e32 v11, v119, v35
	v_fmac_f32_e32 v12, v119, v39
	v_fmac_f32_e32 v13, v119, v43
	v_fmac_f32_e32 v14, v119, v47
	v_fmac_f32_e32 v15, v119, v51
	v_fmac_f32_e32 v0, v119, v59
	ds_read_b128 v[52:55], v98 offset:16
	ds_read_b128 v[24:27], v98 offset:4112
	ds_read_b128 v[28:31], v98 offset:8208
	ds_read_b128 v[32:35], v98 offset:12304
	ds_read_b128 v[36:39], v98 offset:16400
	ds_read_b128 v[40:43], v98 offset:20496
	ds_read_b128 v[44:47], v98 offset:24592
	ds_read_b128 v[48:51], v98 offset:28688
	ds_read_b128 v[56:59], v98 offset:32784
	s_waitcnt lgkmcnt(0)
	v_fmac_f32_e32 v8, v120, v52
	v_fmac_f32_e32 v9, v120, v24
	v_fmac_f32_e32 v10, v120, v28
	v_fmac_f32_e32 v11, v120, v32
	v_fmac_f32_e32 v12, v120, v36
	v_fmac_f32_e32 v13, v120, v40
	v_fmac_f32_e32 v14, v120, v44
	v_fmac_f32_e32 v15, v120, v48
	v_fmac_f32_e32 v0, v120, v56
	v_fmac_f32_e32 v8, v121, v53
	v_fmac_f32_e32 v9, v121, v25
	v_fmac_f32_e32 v10, v121, v29
	v_fmac_f32_e32 v11, v121, v33
	v_fmac_f32_e32 v12, v121, v37
	v_fmac_f32_e32 v13, v121, v41
	v_fmac_f32_e32 v14, v121, v45
	v_fmac_f32_e32 v15, v121, v49
	v_fmac_f32_e32 v0, v121, v57
	v_fmac_f32_e32 v8, v122, v54
	v_fmac_f32_e32 v9, v122, v26
	v_fmac_f32_e32 v10, v122, v30
	v_fmac_f32_e32 v11, v122, v34
	v_fmac_f32_e32 v12, v122, v38
	v_fmac_f32_e32 v13, v122, v42
	v_fmac_f32_e32 v14, v122, v46
	v_fmac_f32_e32 v15, v122, v50
	v_fmac_f32_e32 v0, v122, v58
	v_fmac_f32_e32 v8, v123, v55
	v_fmac_f32_e32 v9, v123, v27
	v_fmac_f32_e32 v10, v123, v31
	v_fmac_f32_e32 v11, v123, v35
	v_fmac_f32_e32 v12, v123, v39
	v_fmac_f32_e32 v13, v123, v43
	v_fmac_f32_e32 v14, v123, v47
	v_fmac_f32_e32 v15, v123, v51
	v_fmac_f32_e32 v0, v123, v59
	ds_read_b128 v[52:55], v98 offset:32
	ds_read_b128 v[24:27], v98 offset:4128
	ds_read_b128 v[28:31], v98 offset:8224
	ds_read_b128 v[32:35], v98 offset:12320
	ds_read_b128 v[36:39], v98 offset:16416
	ds_read_b128 v[40:43], v98 offset:20512
	ds_read_b128 v[44:47], v98 offset:24608
	ds_read_b128 v[48:51], v98 offset:28704
	ds_read_b128 v[56:59], v98 offset:32800
	s_waitcnt lgkmcnt(0)
	v_fmac_f32_e32 v8, v124, v52
	v_fmac_f32_e32 v9, v124, v24
	v_fmac_f32_e32 v10, v124, v28
	v_fmac_f32_e32 v11, v124, v32
	v_fmac_f32_e32 v12, v124, v36
	v_fmac_f32_e32 v13, v124, v40
	v_fmac_f32_e32 v14, v124, v44
	v_fmac_f32_e32 v15, v124, v48
	v_fmac_f32_e32 v0, v124, v56
	v_fmac_f32_e32 v8, v125, v53
	v_fmac_f32_e32 v9, v125, v25
	v_fmac_f32_e32 v10, v125, v29
	v_fmac_f32_e32 v11, v125, v33
	v_fmac_f32_e32 v12, v125, v37
	v_fmac_f32_e32 v13, v125, v41
	v_fmac_f32_e32 v14, v125, v45
	v_fmac_f32_e32 v15, v125, v49
	v_fmac_f32_e32 v0, v125, v57
	v_fmac_f32_e32 v8, v126, v54
	v_fmac_f32_e32 v9, v126, v26
	v_fmac_f32_e32 v10, v126, v30
	v_fmac_f32_e32 v11, v126, v34
	v_fmac_f32_e32 v12, v126, v38
	v_fmac_f32_e32 v13, v126, v42
	v_fmac_f32_e32 v14, v126, v46
	v_fmac_f32_e32 v15, v126, v50
	v_fmac_f32_e32 v0, v126, v58
	v_fmac_f32_e32 v8, v127, v55
	v_fmac_f32_e32 v9, v127, v27
	v_fmac_f32_e32 v10, v127, v31
	v_fmac_f32_e32 v11, v127, v35
	v_fmac_f32_e32 v12, v127, v39
	v_fmac_f32_e32 v13, v127, v43
	v_fmac_f32_e32 v14, v127, v47
	v_fmac_f32_e32 v15, v127, v51
	v_fmac_f32_e32 v0, v127, v59
	ds_read_b128 v[52:55], v98 offset:48
	ds_read_b128 v[24:27], v98 offset:4144
	ds_read_b128 v[28:31], v98 offset:8240
	ds_read_b128 v[32:35], v98 offset:12336
	ds_read_b128 v[36:39], v98 offset:16432
	ds_read_b128 v[40:43], v98 offset:20528
	ds_read_b128 v[44:47], v98 offset:24624
	ds_read_b128 v[48:51], v98 offset:28720
	ds_read_b128 v[56:59], v98 offset:32816
	s_waitcnt lgkmcnt(0)
	v_fmac_f32_e32 v8, v128, v52
	v_fmac_f32_e32 v9, v128, v24
	v_fmac_f32_e32 v10, v128, v28
	v_fmac_f32_e32 v11, v128, v32
	v_fmac_f32_e32 v12, v128, v36
	v_fmac_f32_e32 v13, v128, v40
	v_fmac_f32_e32 v14, v128, v44
	v_fmac_f32_e32 v15, v128, v48
	v_fmac_f32_e32 v0, v128, v56
	v_fmac_f32_e32 v8, v129, v53
	v_fmac_f32_e32 v9, v129, v25
	v_fmac_f32_e32 v10, v129, v29
	v_fmac_f32_e32 v11, v129, v33
	v_fmac_f32_e32 v12, v129, v37
	v_fmac_f32_e32 v13, v129, v41
	v_fmac_f32_e32 v14, v129, v45
	v_fmac_f32_e32 v15, v129, v49
	v_fmac_f32_e32 v0, v129, v57
	v_fmac_f32_e32 v8, v130, v54
	v_fmac_f32_e32 v9, v130, v26
	v_fmac_f32_e32 v10, v130, v30
	v_fmac_f32_e32 v11, v130, v34
	v_fmac_f32_e32 v12, v130, v38
	v_fmac_f32_e32 v13, v130, v42
	v_fmac_f32_e32 v14, v130, v46
	v_fmac_f32_e32 v15, v130, v50
	v_fmac_f32_e32 v0, v130, v58
	v_fmac_f32_e32 v8, v131, v55
	v_fmac_f32_e32 v9, v131, v27
	v_fmac_f32_e32 v10, v131, v31
	v_fmac_f32_e32 v11, v131, v35
	v_fmac_f32_e32 v12, v131, v39
	v_fmac_f32_e32 v13, v131, v43
	v_fmac_f32_e32 v14, v131, v47
	v_fmac_f32_e32 v15, v131, v51
	v_fmac_f32_e32 v0, v131, v59
	v_add_u32_e32 v98, 64, v98
	s_add_i32 s13, s13, -1
	s_cmp_lg_u32 s13, 0
	s_cbranch_scc1 .Lmods_loop
	global_load_dword v116, v99, s[56:57]
	s_add_u32 s56, s56, 0x6000
	s_addc_u32 s57, s57, 0
	global_load_dword v117, v99, s[56:57]
	s_add_u32 s56, s56, 0x6000
	s_addc_u32 s57, s57, 0
	global_load_dword v118, v99, s[56:57]
	s_add_u32 s56, s56, 0x6000
	s_addc_u32 s57, s57, 0
	global_load_dword v119, v99, s[56:57]
	s_add_u32 s56, s56, 0x6000
	s_addc_u32 s57, s57, 0
	global_load_dword v120, v99, s[56:57]
	s_add_u32 s56, s56, 0x6000
	s_addc_u32 s57, s57, 0
	global_load_dword v121, v99, s[56:57]
	s_add_u32 s56, s56, 0x6000
	s_addc_u32 s57, s57, 0
	global_load_dword v122, v99, s[56:57]
	s_add_u32 s56, s56, 0x6000
	s_addc_u32 s57, s57, 0
	global_load_dword v123, v99, s[56:57]
	s_add_u32 s56, s56, 0x6000
	s_addc_u32 s57, s57, 0
	global_load_dword v124, v99, s[56:57]
	s_add_u32 s56, s56, 0x6000
	s_addc_u32 s57, s57, 0
	global_load_dword v125, v99, s[56:57]
	s_add_u32 s56, s56, 0x6000
	s_addc_u32 s57, s57, 0
	global_load_dword v126, v99, s[56:57]
	s_add_u32 s56, s56, 0x6000
	s_addc_u32 s57, s57, 0
	global_load_dword v127, v99, s[56:57]
	s_add_u32 s56, s56, 0x6000
	s_addc_u32 s57, s57, 0
	global_load_dword v128, v99, s[56:57]
	s_add_u32 s56, s56, 0x6000
	s_addc_u32 s57, s57, 0
	global_load_dword v129, v99, s[56:57]
	s_add_u32 s56, s56, 0x6000
	s_addc_u32 s57, s57, 0
	global_load_dword v130, v99, s[56:57]
	s_add_u32 s56, s56, 0x6000
	s_addc_u32 s57, s57, 0
	global_load_dword v131, v99, s[56:57]
	s_add_u32 s56, s56, 0x6000
	s_addc_u32 s57, s57, 0
	s_waitcnt vmcnt(16)
	ds_read_b128 v[52:55], v98
	ds_read_b128 v[24:27], v98 offset:4096
	ds_read_b128 v[28:31], v98 offset:8192
	ds_read_b128 v[32:35], v98 offset:12288
	ds_read_b128 v[36:39], v98 offset:16384
	ds_read_b128 v[40:43], v98 offset:20480
	ds_read_b128 v[44:47], v98 offset:24576
	ds_read_b128 v[48:51], v98 offset:28672
	ds_read_b128 v[56:59], v98 offset:32768
	s_waitcnt lgkmcnt(0)
	v_fmac_f32_e32 v8, v100, v52
	v_fmac_f32_e32 v9, v100, v24
	v_fmac_f32_e32 v10, v100, v28
	v_fmac_f32_e32 v11, v100, v32
	v_fmac_f32_e32 v12, v100, v36
	v_fmac_f32_e32 v13, v100, v40
	v_fmac_f32_e32 v14, v100, v44
	v_fmac_f32_e32 v15, v100, v48
	v_fmac_f32_e32 v0, v100, v56
	v_fmac_f32_e32 v8, v101, v53
	v_fmac_f32_e32 v9, v101, v25
	v_fmac_f32_e32 v10, v101, v29
	v_fmac_f32_e32 v11, v101, v33
	v_fmac_f32_e32 v12, v101, v37
	v_fmac_f32_e32 v13, v101, v41
	v_fmac_f32_e32 v14, v101, v45
	v_fmac_f32_e32 v15, v101, v49
	v_fmac_f32_e32 v0, v101, v57
	v_fmac_f32_e32 v8, v102, v54
	v_fmac_f32_e32 v9, v102, v26
	v_fmac_f32_e32 v10, v102, v30
	v_fmac_f32_e32 v11, v102, v34
	v_fmac_f32_e32 v12, v102, v38
	v_fmac_f32_e32 v13, v102, v42
	v_fmac_f32_e32 v14, v102, v46
	v_fmac_f32_e32 v15, v102, v50
	v_fmac_f32_e32 v0, v102, v58
	v_fmac_f32_e32 v8, v103, v55
	v_fmac_f32_e32 v9, v103, v27
	v_fmac_f32_e32 v10, v103, v31
	v_fmac_f32_e32 v11, v103, v35
	v_fmac_f32_e32 v12, v103, v39
	v_fmac_f32_e32 v13, v103, v43
	v_fmac_f32_e32 v14, v103, v47
	v_fmac_f32_e32 v15, v103, v51
	v_fmac_f32_e32 v0, v103, v59
	ds_read_b128 v[52:55], v98 offset:16
	ds_read_b128 v[24:27], v98 offset:4112
	ds_read_b128 v[28:31], v98 offset:8208
	ds_read_b128 v[32:35], v98 offset:12304
	ds_read_b128 v[36:39], v98 offset:16400
	ds_read_b128 v[40:43], v98 offset:20496
	ds_read_b128 v[44:47], v98 offset:24592
	ds_read_b128 v[48:51], v98 offset:28688
	ds_read_b128 v[56:59], v98 offset:32784
	s_waitcnt lgkmcnt(0)
	v_fmac_f32_e32 v8, v104, v52
	v_fmac_f32_e32 v9, v104, v24
	v_fmac_f32_e32 v10, v104, v28
	v_fmac_f32_e32 v11, v104, v32
	v_fmac_f32_e32 v12, v104, v36
	v_fmac_f32_e32 v13, v104, v40
	v_fmac_f32_e32 v14, v104, v44
	v_fmac_f32_e32 v15, v104, v48
	v_fmac_f32_e32 v0, v104, v56
	v_fmac_f32_e32 v8, v105, v53
	v_fmac_f32_e32 v9, v105, v25
	v_fmac_f32_e32 v10, v105, v29
	v_fmac_f32_e32 v11, v105, v33
	v_fmac_f32_e32 v12, v105, v37
	v_fmac_f32_e32 v13, v105, v41
	v_fmac_f32_e32 v14, v105, v45
	v_fmac_f32_e32 v15, v105, v49
	v_fmac_f32_e32 v0, v105, v57
	v_fmac_f32_e32 v8, v106, v54
	v_fmac_f32_e32 v9, v106, v26
	v_fmac_f32_e32 v10, v106, v30
	v_fmac_f32_e32 v11, v106, v34
	v_fmac_f32_e32 v12, v106, v38
	v_fmac_f32_e32 v13, v106, v42
	v_fmac_f32_e32 v14, v106, v46
	v_fmac_f32_e32 v15, v106, v50
	v_fmac_f32_e32 v0, v106, v58
	v_fmac_f32_e32 v8, v107, v55
	v_fmac_f32_e32 v9, v107, v27
	v_fmac_f32_e32 v10, v107, v31
	v_fmac_f32_e32 v11, v107, v35
	v_fmac_f32_e32 v12, v107, v39
	v_fmac_f32_e32 v13, v107, v43
	v_fmac_f32_e32 v14, v107, v47
	v_fmac_f32_e32 v15, v107, v51
	v_fmac_f32_e32 v0, v107, v59
	ds_read_b128 v[52:55], v98 offset:32
	ds_read_b128 v[24:27], v98 offset:4128
	ds_read_b128 v[28:31], v98 offset:8224
	ds_read_b128 v[32:35], v98 offset:12320
	ds_read_b128 v[36:39], v98 offset:16416
	ds_read_b128 v[40:43], v98 offset:20512
	ds_read_b128 v[44:47], v98 offset:24608
	ds_read_b128 v[48:51], v98 offset:28704
	ds_read_b128 v[56:59], v98 offset:32800
	s_waitcnt lgkmcnt(0)
	v_fmac_f32_e32 v8, v108, v52
	v_fmac_f32_e32 v9, v108, v24
	v_fmac_f32_e32 v10, v108, v28
	v_fmac_f32_e32 v11, v108, v32
	v_fmac_f32_e32 v12, v108, v36
	v_fmac_f32_e32 v13, v108, v40
	v_fmac_f32_e32 v14, v108, v44
	v_fmac_f32_e32 v15, v108, v48
	v_fmac_f32_e32 v0, v108, v56
	v_fmac_f32_e32 v8, v109, v53
	v_fmac_f32_e32 v9, v109, v25
	v_fmac_f32_e32 v10, v109, v29
	v_fmac_f32_e32 v11, v109, v33
	v_fmac_f32_e32 v12, v109, v37
	v_fmac_f32_e32 v13, v109, v41
	v_fmac_f32_e32 v14, v109, v45
	v_fmac_f32_e32 v15, v109, v49
	v_fmac_f32_e32 v0, v109, v57
	v_fmac_f32_e32 v8, v110, v54
	v_fmac_f32_e32 v9, v110, v26
	v_fmac_f32_e32 v10, v110, v30
	v_fmac_f32_e32 v11, v110, v34
	v_fmac_f32_e32 v12, v110, v38
	v_fmac_f32_e32 v13, v110, v42
	v_fmac_f32_e32 v14, v110, v46
	v_fmac_f32_e32 v15, v110, v50
	v_fmac_f32_e32 v0, v110, v58
	v_fmac_f32_e32 v8, v111, v55
	v_fmac_f32_e32 v9, v111, v27
	v_fmac_f32_e32 v10, v111, v31
	v_fmac_f32_e32 v11, v111, v35
	v_fmac_f32_e32 v12, v111, v39
	v_fmac_f32_e32 v13, v111, v43
	v_fmac_f32_e32 v14, v111, v47
	v_fmac_f32_e32 v15, v111, v51
	v_fmac_f32_e32 v0, v111, v59
	ds_read_b128 v[52:55], v98 offset:48
	ds_read_b128 v[24:27], v98 offset:4144
	ds_read_b128 v[28:31], v98 offset:8240
	ds_read_b128 v[32:35], v98 offset:12336
	ds_read_b128 v[36:39], v98 offset:16432
	ds_read_b128 v[40:43], v98 offset:20528
	ds_read_b128 v[44:47], v98 offset:24624
	ds_read_b128 v[48:51], v98 offset:28720
	ds_read_b128 v[56:59], v98 offset:32816
	s_waitcnt lgkmcnt(0)
	v_fmac_f32_e32 v8, v112, v52
	v_fmac_f32_e32 v9, v112, v24
	v_fmac_f32_e32 v10, v112, v28
	v_fmac_f32_e32 v11, v112, v32
	v_fmac_f32_e32 v12, v112, v36
	v_fmac_f32_e32 v13, v112, v40
	v_fmac_f32_e32 v14, v112, v44
	v_fmac_f32_e32 v15, v112, v48
	v_fmac_f32_e32 v0, v112, v56
	v_fmac_f32_e32 v8, v113, v53
	v_fmac_f32_e32 v9, v113, v25
	v_fmac_f32_e32 v10, v113, v29
	v_fmac_f32_e32 v11, v113, v33
	v_fmac_f32_e32 v12, v113, v37
	v_fmac_f32_e32 v13, v113, v41
	v_fmac_f32_e32 v14, v113, v45
	v_fmac_f32_e32 v15, v113, v49
	v_fmac_f32_e32 v0, v113, v57
	v_fmac_f32_e32 v8, v114, v54
	v_fmac_f32_e32 v9, v114, v26
	v_fmac_f32_e32 v10, v114, v30
	v_fmac_f32_e32 v11, v114, v34
	v_fmac_f32_e32 v12, v114, v38
	v_fmac_f32_e32 v13, v114, v42
	v_fmac_f32_e32 v14, v114, v46
	v_fmac_f32_e32 v15, v114, v50
	v_fmac_f32_e32 v0, v114, v58
	v_fmac_f32_e32 v8, v115, v55
	v_fmac_f32_e32 v9, v115, v27
	v_fmac_f32_e32 v10, v115, v31
	v_fmac_f32_e32 v11, v115, v35
	v_fmac_f32_e32 v12, v115, v39
	v_fmac_f32_e32 v13, v115, v43
	v_fmac_f32_e32 v14, v115, v47
	v_fmac_f32_e32 v15, v115, v51
	v_fmac_f32_e32 v0, v115, v59
	v_add_u32_e32 v98, 64, v98
	s_waitcnt vmcnt(0)
	ds_read_b128 v[52:55], v98
	ds_read_b128 v[24:27], v98 offset:4096
	ds_read_b128 v[28:31], v98 offset:8192
	ds_read_b128 v[32:35], v98 offset:12288
	ds_read_b128 v[36:39], v98 offset:16384
	ds_read_b128 v[40:43], v98 offset:20480
	ds_read_b128 v[44:47], v98 offset:24576
	ds_read_b128 v[48:51], v98 offset:28672
	ds_read_b128 v[56:59], v98 offset:32768
	s_waitcnt lgkmcnt(0)
	v_fmac_f32_e32 v8, v116, v52
	v_fmac_f32_e32 v9, v116, v24
	v_fmac_f32_e32 v10, v116, v28
	v_fmac_f32_e32 v11, v116, v32
	v_fmac_f32_e32 v12, v116, v36
	v_fmac_f32_e32 v13, v116, v40
	v_fmac_f32_e32 v14, v116, v44
	v_fmac_f32_e32 v15, v116, v48
	v_fmac_f32_e32 v0, v116, v56
	v_fmac_f32_e32 v8, v117, v53
	v_fmac_f32_e32 v9, v117, v25
	v_fmac_f32_e32 v10, v117, v29
	v_fmac_f32_e32 v11, v117, v33
	v_fmac_f32_e32 v12, v117, v37
	v_fmac_f32_e32 v13, v117, v41
	v_fmac_f32_e32 v14, v117, v45
	v_fmac_f32_e32 v15, v117, v49
	v_fmac_f32_e32 v0, v117, v57
	v_fmac_f32_e32 v8, v118, v54
	v_fmac_f32_e32 v9, v118, v26
	v_fmac_f32_e32 v10, v118, v30
	v_fmac_f32_e32 v11, v118, v34
	v_fmac_f32_e32 v12, v118, v38
	v_fmac_f32_e32 v13, v118, v42
	v_fmac_f32_e32 v14, v118, v46
	v_fmac_f32_e32 v15, v118, v50
	v_fmac_f32_e32 v0, v118, v58
	v_fmac_f32_e32 v8, v119, v55
	v_fmac_f32_e32 v9, v119, v27
	v_fmac_f32_e32 v10, v119, v31
	v_fmac_f32_e32 v11, v119, v35
	v_fmac_f32_e32 v12, v119, v39
	v_fmac_f32_e32 v13, v119, v43
	v_fmac_f32_e32 v14, v119, v47
	v_fmac_f32_e32 v15, v119, v51
	v_fmac_f32_e32 v0, v119, v59
	ds_read_b128 v[52:55], v98 offset:16
	ds_read_b128 v[24:27], v98 offset:4112
	ds_read_b128 v[28:31], v98 offset:8208
	ds_read_b128 v[32:35], v98 offset:12304
	ds_read_b128 v[36:39], v98 offset:16400
	ds_read_b128 v[40:43], v98 offset:20496
	ds_read_b128 v[44:47], v98 offset:24592
	ds_read_b128 v[48:51], v98 offset:28688
	ds_read_b128 v[56:59], v98 offset:32784
	s_waitcnt lgkmcnt(0)
	v_fmac_f32_e32 v8, v120, v52
	v_fmac_f32_e32 v9, v120, v24
	v_fmac_f32_e32 v10, v120, v28
	v_fmac_f32_e32 v11, v120, v32
	v_fmac_f32_e32 v12, v120, v36
	v_fmac_f32_e32 v13, v120, v40
	v_fmac_f32_e32 v14, v120, v44
	v_fmac_f32_e32 v15, v120, v48
	v_fmac_f32_e32 v0, v120, v56
	v_fmac_f32_e32 v8, v121, v53
	v_fmac_f32_e32 v9, v121, v25
	v_fmac_f32_e32 v10, v121, v29
	v_fmac_f32_e32 v11, v121, v33
	v_fmac_f32_e32 v12, v121, v37
	v_fmac_f32_e32 v13, v121, v41
	v_fmac_f32_e32 v14, v121, v45
	v_fmac_f32_e32 v15, v121, v49
	v_fmac_f32_e32 v0, v121, v57
	v_fmac_f32_e32 v8, v122, v54
	v_fmac_f32_e32 v9, v122, v26
	v_fmac_f32_e32 v10, v122, v30
	v_fmac_f32_e32 v11, v122, v34
	v_fmac_f32_e32 v12, v122, v38
	v_fmac_f32_e32 v13, v122, v42
	v_fmac_f32_e32 v14, v122, v46
	v_fmac_f32_e32 v15, v122, v50
	v_fmac_f32_e32 v0, v122, v58
	v_fmac_f32_e32 v8, v123, v55
	v_fmac_f32_e32 v9, v123, v27
	v_fmac_f32_e32 v10, v123, v31
	v_fmac_f32_e32 v11, v123, v35
	v_fmac_f32_e32 v12, v123, v39
	v_fmac_f32_e32 v13, v123, v43
	v_fmac_f32_e32 v14, v123, v47
	v_fmac_f32_e32 v15, v123, v51
	v_fmac_f32_e32 v0, v123, v59
	ds_read_b128 v[52:55], v98 offset:32
	ds_read_b128 v[24:27], v98 offset:4128
	ds_read_b128 v[28:31], v98 offset:8224
	ds_read_b128 v[32:35], v98 offset:12320
	ds_read_b128 v[36:39], v98 offset:16416
	ds_read_b128 v[40:43], v98 offset:20512
	ds_read_b128 v[44:47], v98 offset:24608
	ds_read_b128 v[48:51], v98 offset:28704
	ds_read_b128 v[56:59], v98 offset:32800
	s_waitcnt lgkmcnt(0)
	v_fmac_f32_e32 v8, v124, v52
	v_fmac_f32_e32 v9, v124, v24
	v_fmac_f32_e32 v10, v124, v28
	v_fmac_f32_e32 v11, v124, v32
	v_fmac_f32_e32 v12, v124, v36
	v_fmac_f32_e32 v13, v124, v40
	v_fmac_f32_e32 v14, v124, v44
	v_fmac_f32_e32 v15, v124, v48
	v_fmac_f32_e32 v0, v124, v56
	v_fmac_f32_e32 v8, v125, v53
	v_fmac_f32_e32 v9, v125, v25
	v_fmac_f32_e32 v10, v125, v29
	v_fmac_f32_e32 v11, v125, v33
	v_fmac_f32_e32 v12, v125, v37
	v_fmac_f32_e32 v13, v125, v41
	v_fmac_f32_e32 v14, v125, v45
	v_fmac_f32_e32 v15, v125, v49
	v_fmac_f32_e32 v0, v125, v57
	v_fmac_f32_e32 v8, v126, v54
	v_fmac_f32_e32 v9, v126, v26
	v_fmac_f32_e32 v10, v126, v30
	v_fmac_f32_e32 v11, v126, v34
	v_fmac_f32_e32 v12, v126, v38
	v_fmac_f32_e32 v13, v126, v42
	v_fmac_f32_e32 v14, v126, v46
	v_fmac_f32_e32 v15, v126, v50
	v_fmac_f32_e32 v0, v126, v58
	v_fmac_f32_e32 v8, v127, v55
	v_fmac_f32_e32 v9, v127, v27
	v_fmac_f32_e32 v10, v127, v31
	v_fmac_f32_e32 v11, v127, v35
	v_fmac_f32_e32 v12, v127, v39
	v_fmac_f32_e32 v13, v127, v43
	v_fmac_f32_e32 v14, v127, v47
	v_fmac_f32_e32 v15, v127, v51
	v_fmac_f32_e32 v0, v127, v59
	ds_read_b128 v[52:55], v98 offset:48
	ds_read_b128 v[24:27], v98 offset:4144
	ds_read_b128 v[28:31], v98 offset:8240
	ds_read_b128 v[32:35], v98 offset:12336
	ds_read_b128 v[36:39], v98 offset:16432
	ds_read_b128 v[40:43], v98 offset:20528
	ds_read_b128 v[44:47], v98 offset:24624
	ds_read_b128 v[48:51], v98 offset:28720
	ds_read_b128 v[56:59], v98 offset:32816
	s_waitcnt lgkmcnt(0)
	v_fmac_f32_e32 v8, v128, v52
	v_fmac_f32_e32 v9, v128, v24
	v_fmac_f32_e32 v10, v128, v28
	v_fmac_f32_e32 v11, v128, v32
	v_fmac_f32_e32 v12, v128, v36
	v_fmac_f32_e32 v13, v128, v40
	v_fmac_f32_e32 v14, v128, v44
	v_fmac_f32_e32 v15, v128, v48
	v_fmac_f32_e32 v0, v128, v56
	v_fmac_f32_e32 v8, v129, v53
	v_fmac_f32_e32 v9, v129, v25
	v_fmac_f32_e32 v10, v129, v29
	v_fmac_f32_e32 v11, v129, v33
	v_fmac_f32_e32 v12, v129, v37
	v_fmac_f32_e32 v13, v129, v41
	v_fmac_f32_e32 v14, v129, v45
	v_fmac_f32_e32 v15, v129, v49
	v_fmac_f32_e32 v0, v129, v57
	v_fmac_f32_e32 v8, v130, v54
	v_fmac_f32_e32 v9, v130, v26
	v_fmac_f32_e32 v10, v130, v30
	v_fmac_f32_e32 v11, v130, v34
	v_fmac_f32_e32 v12, v130, v38
	v_fmac_f32_e32 v13, v130, v42
	v_fmac_f32_e32 v14, v130, v46
	v_fmac_f32_e32 v15, v130, v50
	v_fmac_f32_e32 v0, v130, v58
	v_fmac_f32_e32 v8, v131, v55
	v_fmac_f32_e32 v9, v131, v27
	v_fmac_f32_e32 v10, v131, v31
	v_fmac_f32_e32 v11, v131, v35
	v_fmac_f32_e32 v12, v131, v39
	v_fmac_f32_e32 v13, v131, v43
	v_fmac_f32_e32 v14, v131, v47
	v_fmac_f32_e32 v15, v131, v51
	v_fmac_f32_e32 v0, v131, v59
	v_add_u32_e32 v98, 64, v98
	ds_write2st64_b32 v22, v8, v9 offset0:144 offset1:145
	ds_write2st64_b32 v22, v10, v11 offset0:146 offset1:147
	ds_write2st64_b32 v22, v12, v13 offset0:148 offset1:149
	ds_write2st64_b32 v22, v14, v15 offset0:150 offset1:151
	ds_write_b32 v22, v0 offset:38912
	s_waitcnt lgkmcnt(0)
	s_barrier
	s_and_saveexec_b64 s[10:11], s[0:1]
	s_cbranch_execz .LBB0_21
	v_lshl_or_b32 v6, s40, 6, v217
	v_readlane_b32 s56, v254, 12
	v_ashrrev_i32_e32 v7, 31, v6
	v_readlane_b32 s58, v254, 14
	v_readlane_b32 s59, v254, 15
	s_mov_b64 s[12:13], 0
	v_mov_b32_e32 v8, v21
	v_lshl_add_u64 v[6:7], v[6:7], 2, s[58:59]
	v_mov_b32_e32 v0, v20
	v_mov_b32_e32 v10, v19
	v_readlane_b32 s57, v254, 13
	v_readlane_b32 s60, v254, 16
	v_readlane_b32 s61, v254, 17
	v_readlane_b32 s62, v254, 18
	v_readlane_b32 s63, v254, 19
	v_readlane_b32 s64, v254, 20
	v_readlane_b32 s65, v254, 21
	v_readlane_b32 s66, v254, 22
	v_readlane_b32 s67, v254, 23
	v_readlane_b32 s68, v254, 24
	v_readlane_b32 s69, v254, 25
	v_readlane_b32 s70, v254, 26
	v_readlane_b32 s71, v254, 27

.LBB0_690:
	s_mov_b32 s100, 0
	s_mov_b32 s98, s101
	s_movk_i32 s99, 0x200
	s_cmp_lt_i32 s82, 6
	s_cselect_b64 s[4:5], -1, 0
	s_and_b64 s[6:7], s[4:5], s[0:1]
	s_andn2_b64 vcc, exec, s[6:7]
	s_cbranch_vccnz .LBB0_711
.Lp5_body:
	s_cmp_ge_i32 s98, s99
	v_readfirstlane_b32 s1, v210
	s_cbranch_scc1 .LBB0_711
	v_lshlrev_b32_e32 v11, 4, v210
	v_add_u32_e32 v1, 0x2000, v11
	v_lshrrev_b32_e32 v1, 7, v1
	v_bfe_u32 v2, v210, 2, 4
	s_movk_i32 s0, 0xf0
	v_lshrrev_b32_e32 v0, 3, v210
	v_and_or_b32 v1, v1, s0, v2
	s_movk_i32 s0, 0x70
	s_ashr_i32 s35, s98, 31
	v_and_or_b32 v0, v0, s0, v2
	s_lshr_b32 s0, s35, 29
	s_add_i32 s0, s98, s0
	s_lshr_b32 s5, s1, 6
	s_ashr_i32 s8, s0, 3
	s_and_b32 s0, s0, -8
	s_lshr_b32 s4, s1, 8
	s_lshl_b32 s3, s5, 10
	s_sub_i32 s0, s98, s0
	s_cmp_lt_i32 s0, 0
	s_movk_i32 s52, 0x51
	s_cselect_b32 s9, s52, 0x50
	s_mul_i32 s0, s0, s9
	s_add_i32 s0, s0, s8
	s_ashr_i32 s8, s0, 31
	s_lshr_b32 s8, s8, 28
	s_add_i32 s8, s0, s8
	s_ashr_i32 s9, s8, 4
	s_and_b32 s8, s8, -16
	s_sub_i32 s8, s0, s8
	s_bfe_i32 s0, s8, 0x80000
	s_bfe_u32 s0, s0, 0x2000d
	s_add_i32 s10, s8, s0
	s_bfe_i32 s0, s10, 0x80000
	s_and_b32 s10, s10, 0xfc
	s_sext_i32_i16 s0, s0
	s_sub_i32 s8, s8, s10
	s_lshl_b32 s9, s9, 2
	s_lshr_b32 s0, s0, 2
	s_sext_i32_i8 s8, s8
	s_add_i32 s48, s9, s8
	s_bfe_i64 s[8:9], s[0:1], 0x100000
	v_and_b32_e32 v3, 32, v210
	s_lshl_b64 s[8:9], s[8:9], 19
	v_bitop3_b32 v8, v11, v3, 48 bitop3:0x6c
	v_and_b32_e32 v9, 64, v210
	s_add_u32 s20, s88, s8
	v_or_b32_e32 v3, v8, v9
	s_addc_u32 s21, s89, s9
	s_add_i32 s53, s3, 0
	v_lshl_or_b32 v140, v0, 11, v3
	s_add_i32 m0, s53, 0x10000
	v_lshl_or_b32 v136, v1, 11, v3
	global_load_lds_dwordx4 v140, s[20:21]
	s_add_i32 m0, s53, 0x12000
	s_add_u32 s8, s20, 0x40000
	global_load_lds_dwordx4 v136, s[20:21]
	s_addc_u32 s9, s21, 0
	s_add_i32 m0, s53, 0x14000
	s_mul_i32 s11, s48, 0xc0000
	global_load_lds_dwordx4 v140, s[8:9]
	s_add_i32 m0, s53, 0x16000
	s_mul_hi_i32 s10, s48, 0xc0000
	s_add_u32 s46, s24, s11
	s_waitcnt lgkmcnt(0)
	v_mul_u32_u24_e32 v12, 0xc00, v0
	s_addc_u32 s47, s25, s10
	s_add_i32 s54, s53, 0x2000
	v_mul_u32_u24_e32 v10, 0xc00, v1
	v_or_b32_e32 v142, v3, v12
	global_load_lds_dwordx4 v136, s[8:9]
	s_mov_b32 m0, s53
	s_add_u32 s8, s46, 0x60000
	v_or_b32_e32 v138, v10, v3
	global_load_lds_dwordx4 v142, s[46:47]
	s_mov_b32 m0, s54
	s_addc_u32 s9, s47, 0
	s_add_i32 s55, s53, 0x4000
	global_load_lds_dwordx4 v138, s[46:47]
	s_mov_b32 m0, s55
	s_add_i32 s56, s53, 0x6000
	global_load_lds_dwordx4 v142, s[8:9]
	s_mov_b32 m0, s56
	v_mov_b32_e32 v145, 0
	global_load_lds_dwordx4 v138, s[8:9]
	v_mov_b32_e32 v141, v145
	v_mov_b32_e32 v137, v145
	v_mov_b32_e32 v143, v145
	v_mov_b32_e32 v139, v145
	s_cmp_eq_u32 s4, 1
	s_mov_b32 s9, 0
	s_mov_b32 s57, 0x10000
	v_lshl_add_u64 v[6:7], s[20:21], 0, v[140:141]
	v_lshl_add_u64 v[4:5], s[20:21], 0, v[136:137]
	v_lshl_add_u64 v[2:3], s[46:47], 0, v[142:143]
	s_cselect_b64 s[10:11], -1, 0
	s_cmp_lg_u32 s4, 1
	v_lshl_add_u64 v[0:1], s[46:47], 0, v[138:139]
	s_cbranch_scc1 .LBB0_694
	s_barrier
.LBB0_694:
	s_mov_b64 s[12:13], 0x80
	s_and_b32 s5, s5, 3
	s_add_i32 m0, s53, 0x18000
	v_lshl_add_u64 v[6:7], v[6:7], 0, s[12:13]
	s_lshl_b32 s58, s4, 6
	s_lshl_b32 s8, s4, 13
	s_lshl_b32 s28, s5, 12
	s_waitcnt vmcnt(2)
	s_barrier
	global_load_lds_dwordx4 v[6:7], off
	v_lshl_add_u64 v[4:5], v[4:5], 0, s[12:13]
	s_add_i32 m0, s53, 0x1a000
	s_add_i32 s59, s53, 0x8000
	s_add_i32 s60, s53, 0xa000
	global_load_lds_dwordx4 v[4:5], off
	v_lshl_add_u64 v[2:3], v[2:3], 0, s[12:13]
	s_mov_b32 m0, s59
	s_add_u32 s14, s20, 0x40080
	global_load_lds_dwordx4 v[2:3], off
	v_lshl_add_u64 v[0:1], v[0:1], 0, s[12:13]
	s_mov_b32 m0, s60
	s_addc_u32 s15, s21, 0
	global_load_lds_dwordx4 v[0:1], off
	s_add_i32 m0, s53, 0x1c000
	v_lshl_add_u64 v[0:1], s[14:15], 0, v[140:141]
	global_load_lds_dwordx4 v[0:1], off
	v_lshl_add_u64 v[0:1], s[14:15], 0, v[136:137]
	s_add_i32 m0, s53, 0x1e000
	v_and_b32_e32 v160, 15, v210
	global_load_lds_dwordx4 v[0:1], off
	v_bfe_u32 v1, v210, 4, 2
	v_lshlrev_b32_e32 v2, 4, v1
	v_lshlrev_b32_e32 v3, 2, v210
	v_lshl_or_b32 v0, v160, 6, v2
	v_and_b32_e32 v3, 32, v3
	v_bitop3_b32 v4, v0, s8, v3 bitop3:0xde
	s_lshl_b32 s8, s5, 6
	s_sext_i32_i8 s49, s0
	v_lshlrev_b32_e32 v0, 6, v210
	s_movk_i32 s0, 0x3c0
	s_cmpk_lt_u32 s1, 0x100
	v_and_or_b32 v0, v0, s0, v2
	s_cselect_b64 s[14:15], -1, 0
	s_lshl_b32 s0, s4, 2
	s_or_b32 s0, s0, s5
	s_mulk_i32 s0, 0x900
	s_add_i32 s0, s0, 0
	s_add_i32 s0, s0, 0x20400
	v_bitop3_b32 v162, s28, v0, v3 bitop3:0xf6
	v_bfe_u32 v163, v210, 3, 3
	s_movk_i32 s1, 0x90
	v_mov_b32_e32 v3, s0
	s_waitcnt vmcnt(6)
	v_lshlrev_b32_e32 v0, 3, v210
	v_mad_u32_u24 v5, v160, s1, v3
	v_mad_u32_u24 v3, v163, s1, v3
	v_add3_u32 v144, v12, v8, v9
	s_mov_b64 s[0:1], 0x60080
	v_and_b32_e32 v0, 56, v0
	v_lshl_or_b32 v164, v1, 3, s8
	v_and_b32_e32 v1, 0x70, v11
	v_lshl_add_u64 v[146:147], v[144:145], 0, s[0:1]
	v_add3_u32 v144, v10, v8, v9
	v_or_b32_e32 v161, s58, v160
	s_ashr_i32 s61, s33, 31
	v_lshl_add_u64 v[148:149], v[144:145], 0, s[0:1]
	v_mov_b32_e32 v150, s99
	v_mov_b32_e32 v151, 0
	v_add_u32_e32 v152, -1, v150
	v_mov_b32_e32 v153, 0
	s_mov_b64 s[28:29], 0x80000
	s_mov_b64 s[30:31], 0x90000
	s_mov_b64 s[36:37], 0xa0000
	s_mov_b64 s[38:39], 0xb0000
	s_add_i32 s62, 0, 0x14000
	v_add_u32_e32 v165, 0, v4
	s_lshl_b32 s8, s8, 1
	v_lshlrev_b32_e32 v144, 1, v0
	v_add_u32_e32 v166, v5, v2
	v_add_u32_e32 v167, v3, v1
	s_mov_b32 s63, 0x4c000
	s_mov_b32 s64, 0x50000
	s_mov_b32 s65, 0x54000
	s_mov_b32 s66, s9
	s_barrier
	s_branch .LBB0_697

.LBB0_697:
	s_add_i32 s66, s66, 1
	s_mul_i32 s0, s66, s61
	s_mul_hi_u32 s1, s66, s33
	s_add_i32 s1, s1, s0
	s_mul_i32 s0, s66, s33
	s_add_u32 s0, s0, s98
	s_addc_u32 s1, s1, s35
	v_cmp_gt_i64_e32 vcc, s[0:1], v[152:153]
	v_cmp_lt_i64_e64 s[4:5], s[0:1], v[150:151]
	s_cbranch_vccnz .LBB0_699
	s_ashr_i32 s1, s0, 31
	s_lshr_b32 s1, s1, 29
	s_add_i32 s1, s0, s1
	s_ashr_i32 s40, s1, 3
	s_and_b32 s1, s1, -8
	s_sub_i32 s0, s0, s1
	s_cmp_lt_i32 s0, 0
	s_cselect_b32 s1, s52, 0x50
	s_mul_i32 s0, s0, s1
	s_add_i32 s0, s0, s40
	s_ashr_i32 s1, s0, 31
	s_lshr_b32 s1, s1, 28
	s_add_i32 s1, s0, s1
	s_ashr_i32 s40, s1, 4
	s_lshl_b32 s41, s40, 2
	s_sub_i32 s40, 0xa0, s41
	s_min_i32 s42, s40, 4
	s_abs_i32 s40, s42
	v_cvt_f32_u32_e32 v0, s40
	s_sub_i32 s44, 0, s40
	s_and_b32 s1, s1, -16
	s_sub_i32 s0, s0, s1
	v_rcp_iflag_f32_e32 v0, v0
	s_abs_i32 s1, s0
	s_xor_b32 s43, s0, s42
	s_ashr_i32 s43, s43, 31
	v_mul_f32_e32 v0, 0x4f7ffffe, v0
	v_cvt_u32_f32_e32 v0, v0
	s_nop 0
	v_readfirstlane_b32 s45, v0
	s_mul_i32 s44, s44, s45
	s_mul_hi_u32 s44, s45, s44
	s_add_i32 s45, s45, s44
	s_mul_hi_u32 s44, s1, s45
	s_mul_i32 s45, s44, s40
	s_sub_i32 s1, s1, s45
	s_add_i32 s50, s44, 1
	s_sub_i32 s45, s1, s40
	s_cmp_ge_u32 s1, s40
	s_cselect_b32 s44, s50, s44
	s_cselect_b32 s1, s45, s1
	s_add_i32 s45, s44, 1
	s_cmp_ge_u32 s1, s40
	s_cselect_b32 s1, s45, s44
	s_xor_b32 s1, s1, s43
	s_sub_i32 s40, s1, s43
	s_mul_i32 s1, s40, s42
	s_sub_i32 s0, s0, s1
	s_add_i32 s67, s41, s0

.Lseam5_body:
	s_waitcnt vmcnt(0)
	v_cmp_eq_u32_e32 vcc, 0, v210
	s_waitcnt vmcnt(0) lgkmcnt(0)
	s_barrier
	s_and_saveexec_b64 s[4:5], vcc
	s_cbranch_execz .LBB0_760
	s_add_i32 s3, 0, 0x20200
	v_mov_b32_e32 v0, s3
	s_waitcnt vmcnt(0) expcnt(0) lgkmcnt(0)
	ds_read_b32 v2, v0
	s_add_i32 s3, 0, 0x20204
	v_mov_b32_e32 v0, s3
	ds_read_b32 v0, v0
	s_waitcnt lgkmcnt(1)
	v_cmp_ne_u32_e32 vcc, 0, v2
	s_cbranch_vccnz .LBB0_728
	v_readlane_b32 s6, v254, 8
	v_readlane_b32 s7, v254, 9
	s_load_dwordx2 s[10:11], s[6:7], 0x4
	s_add_u32 s6, s78, 0x1e00200
	s_addc_u32 s7, s79, 0
	s_add_u32 s8, s78, 0x1e00400
	s_addc_u32 s9, s79, 0
	s_waitcnt lgkmcnt(0)
	s_mul_i32 s3, s10, s33
	s_add_u32 s10, s78, 0x1e00500
	s_mul_i32 s3, s3, s11
	s_addc_u32 s11, s79, 0
	s_add_u32 s12, s78, 0x1e00600
	s_addc_u32 s13, s79, 0
	s_add_u32 s14, s78, 0x1e00700
	s_addc_u32 s15, s79, 0
	s_add_u32 s20, s78, 0x1e00800
	s_addc_u32 s21, s79, 0
	s_add_u32 s24, s78, 0x1e00900
	s_addc_u32 s25, s79, 0
	s_add_u32 s26, s78, 0x1e00a00
	s_addc_u32 s27, s79, 0
	s_add_u32 s28, s78, 0x1e00b00
	s_addc_u32 s29, s79, 0
	s_add_u32 s30, s78, 0x1e00c00
	s_addc_u32 s31, s79, 0
	s_add_u32 s36, s78, 0x1e00d00
	s_addc_u32 s37, s79, 0
	s_add_u32 s38, s78, 0x1e00e00
	s_addc_u32 s39, s79, 0
	s_add_u32 s40, s78, 0x1e00f00
	s_addc_u32 s41, s79, 0
	s_add_u32 s42, s78, 0x1e01000
	s_addc_u32 s43, s79, 0
	s_add_u32 s44, s78, 0x1e01100
	s_addc_u32 s45, s79, 0
	s_add_u32 s46, s78, 0x1e01200
	s_addc_u32 s47, s79, 0
	s_add_u32 s48, s78, 0x1e01300
	s_addc_u32 s49, s79, 0
	s_mov_b32 s35, 1
	v_mov_b32_e32 v16, 0
	s_branch .LBB0_716

.LBB0_761:
	s_add_i32 s100, s100, 1
	s_mov_b64 s[0:1], -1
	s_cmp_eq_u32 s100, 1
	s_cbranch_scc0 .Lp56_stage_c
	s_cmpk_lt_u32 s101, 0x80
	s_cbranch_scc0 .Lp56_b_hi
	s_add_i32 s98, s101, 0x200
	s_movk_i32 s99, 0x280
	s_mov_b64 s[6:7], -1
	s_add_u32 s24, s78, 0x17e00000
	s_addc_u32 s25, s79, 0
	s_add_u32 s26, s78, 0xde00000
	s_addc_u32 s27, s79, 0
	s_branch .Lp5_body
.Lp56_b_hi:
	s_sub_i32 s98, s101, 0x80
	s_movk_i32 s99, 0x100
	s_branch .Lp6_gate
.Lp56_stage_c:
	s_movk_i32 s99, 0x200
	s_cmpk_lt_u32 s101, 0x80
	s_cselect_b32 s99, 0x280, s99
	s_cselect_b32 s98, 0x100, 0
	s_add_i32 s98, s98, s101

.Lp6_body:
	s_cmp_ge_i32 s98, s99
	v_readfirstlane_b32 s12, v210
	s_cbranch_scc1 .LBB0_778
	v_lshlrev_b32_e32 v1, 4, v210
	v_add_u32_e32 v8, 0x2000, v1
	v_lshrrev_b32_e32 v2, 7, v8
	v_bfe_u32 v11, v210, 2, 4
	s_movk_i32 s0, 0xf0
	v_lshrrev_b32_e32 v0, 3, v210
	v_and_or_b32 v2, v2, s0, v11
	s_movk_i32 s0, 0x70
	s_ashr_i32 s35, s98, 31
	v_and_or_b32 v0, v0, s0, v11
	s_lshr_b32 s0, s35, 29
	s_add_i32 s0, s98, s0
	s_lshr_b32 s6, s12, 6
	s_ashr_i32 s7, s0, 3
	s_and_b32 s0, s0, -8
	s_lshr_b32 s1, s12, 8
	s_lshl_b32 s3, s6, 10
	s_sub_i32 s0, s98, s0
	s_cmp_lt_i32 s0, 0
	s_movk_i32 s46, 0x51
	s_cselect_b32 s8, s46, 0x50
	s_mul_i32 s0, s0, s8
	s_add_i32 s0, s0, s7
	s_ashr_i32 s7, s0, 31
	s_lshr_b32 s7, s7, 28
	s_add_i32 s7, s0, s7
	s_ashr_i32 s8, s7, 4
	s_and_b32 s7, s7, -16
	s_sub_i32 s7, s0, s7
	s_bfe_i32 s0, s7, 0x80000
	s_bfe_u32 s0, s0, 0x2000d
	s_add_i32 s9, s7, s0
	s_bfe_i32 s0, s9, 0x80000
	s_and_b32 s9, s9, 0xfc
	s_sub_i32 s7, s7, s9
	s_lshl_b32 s8, s8, 2
	s_sext_i32_i16 s0, s0
	s_sext_i32_i8 s7, s7
	s_lshr_b32 s0, s0, 2
	s_add_i32 s20, s8, s7
	s_ashr_i32 s21, s20, 31
	s_bfe_i64 s[10:11], s[0:1], 0x100000
	v_and_b32_e32 v3, 32, v210
	s_lshl_b64 s[8:9], s[20:21], 19
	s_lshl_b64 s[10:11], s[10:11], 19
	v_bitop3_b32 v9, v1, v3, 48 bitop3:0x6c
	s_waitcnt lgkmcnt(0)
	v_and_b32_e32 v10, 64, v210
	s_add_u32 s42, s92, s10
	v_or_b32_e32 v1, v9, v10
	s_addc_u32 s43, s93, s11
	s_add_i32 s21, s3, 0
	v_lshl_or_b32 v146, v0, 11, v1
	s_add_i32 m0, s21, 0x10000
	v_lshl_or_b32 v144, v2, 11, v1
	global_load_lds_dwordx4 v146, s[42:43]
	s_add_i32 m0, s21, 0x12000
	s_add_u32 s10, s42, 0x40000
	global_load_lds_dwordx4 v144, s[42:43]
	s_addc_u32 s11, s43, 0
	s_add_i32 m0, s21, 0x14000
	v_mov_b32_e32 v147, 0
	global_load_lds_dwordx4 v146, s[10:11]
	s_add_i32 m0, s21, 0x16000
	s_add_u32 s40, s94, s8
	s_addc_u32 s41, s95, s9
	s_add_i32 s47, s21, 0x2000
	global_load_lds_dwordx4 v144, s[10:11]
	s_mov_b32 m0, s21
	s_add_u32 s8, s40, 0x40000
	global_load_lds_dwordx4 v146, s[40:41]
	s_mov_b32 m0, s47
	s_addc_u32 s9, s41, 0
	s_add_i32 s48, s21, 0x4000
	global_load_lds_dwordx4 v144, s[40:41]
	s_mov_b32 m0, s48
	s_add_i32 s49, s21, 0x6000
	global_load_lds_dwordx4 v146, s[8:9]
	s_mov_b32 m0, s49
	v_mov_b32_e32 v145, v147
	global_load_lds_dwordx4 v144, s[8:9]
	s_cmp_eq_u32 s1, 1
	s_mov_b32 s7, 0
	s_mov_b32 s50, 0x10000
	v_lshl_add_u64 v[6:7], s[42:43], 0, v[146:147]
	v_lshl_add_u64 v[4:5], s[42:43], 0, v[144:145]
	v_lshl_add_u64 v[0:1], s[40:41], 0, v[146:147]
	s_cselect_b64 s[8:9], -1, 0
	s_cmp_lg_u32 s1, 1
	v_lshl_add_u64 v[2:3], s[40:41], 0, v[144:145]
	s_cbranch_scc1 .LBB0_765
	s_barrier
.LBB0_765:
	s_mov_b64 s[10:11], 0x80
	s_and_b32 s24, s6, 3
	s_add_i32 m0, s21, 0x18000
	v_lshl_add_u64 v[6:7], v[6:7], 0, s[10:11]
	s_lshl_b32 s13, s1, 13
	s_lshl_b32 s25, s24, 12
	s_waitcnt vmcnt(2)
	s_barrier
	global_load_lds_dwordx4 v[6:7], off
	v_lshl_add_u64 v[4:5], v[4:5], 0, s[10:11]
	s_add_i32 m0, s21, 0x1a000
	s_add_i32 s51, s21, 0x8000
	s_add_i32 s52, s21, 0xa000
	global_load_lds_dwordx4 v[4:5], off
	v_lshl_add_u64 v[0:1], v[0:1], 0, s[10:11]
	s_mov_b32 m0, s51
	s_add_u32 s14, s42, 0x40080
	global_load_lds_dwordx4 v[0:1], off
	v_lshl_add_u64 v[0:1], v[2:3], 0, s[10:11]
	s_mov_b32 m0, s52
	s_addc_u32 s15, s43, 0
	global_load_lds_dwordx4 v[0:1], off
	s_add_i32 m0, s21, 0x1c000
	v_lshl_add_u64 v[0:1], s[14:15], 0, v[146:147]
	global_load_lds_dwordx4 v[0:1], off
	v_lshl_add_u64 v[0:1], s[14:15], 0, v[144:145]
	s_add_i32 m0, s21, 0x1e000
	v_lshlrev_b32_e32 v4, 2, v210
	global_load_lds_dwordx4 v[0:1], off
	v_bfe_u32 v1, v210, 4, 2
	v_and_b32_e32 v0, 15, v210
	v_lshlrev_b32_e32 v2, 4, v1
	v_lshl_or_b32 v3, v0, 6, v2
	v_and_b32_e32 v4, 32, v4
	s_cmpk_lt_u32 s12, 0x100
	s_sext_i32_i8 s6, s0
	v_bitop3_b32 v3, v3, s13, v4 bitop3:0xde
	v_lshlrev_b32_e32 v5, 6, v210
	s_movk_i32 s0, 0x3c0
	s_cselect_b64 s[12:13], -1, 0
	s_lshl_b32 s14, s1, 2
	v_and_or_b32 v5, v5, s0, v2
	s_lshl_b32 s0, s24, 6
	s_or_b32 s14, s14, s24
	s_ashr_i32 s55, s33, 31
	v_bitop3_b32 v149, s25, v5, v4 bitop3:0xf6
	s_mulk_i32 s14, 0x900
	v_and_b32_e32 v4, 7, v210
	s_add_u32 s56, s18, 0xfe000000
	v_lshl_or_b32 v160, v1, 3, s0
	v_lshl_or_b32 v148, v4, 3, s0
	s_addc_u32 s57, s19, -1
	s_add_i32 s0, s14, 0
	v_bfe_u32 v1, v210, 3, 3
	s_add_i32 s0, s0, 0x20400
	v_lshlrev_b32_e32 v5, 4, v4
	v_lshl_or_b32 v161, s1, 6, v1
	s_movk_i32 s1, 0x90
	v_mov_b32_e32 v4, s0
	v_mad_u32_u24 v0, v0, s1, v4
	v_mad_u32_u24 v1, v1, s1, v4
	v_lshlrev_b32_e32 v4, 8, v210
	v_and_b32_e32 v4, 0x38000, v4
	v_lshlrev_b32_e32 v6, 11, v11
	v_or3_b32 v4, v9, v4, v6
	v_add_u32_e32 v150, v4, v10
	v_lshlrev_b32_e32 v4, 4, v8
	s_waitcnt vmcnt(6)
	v_and_b32_e32 v4, 0x78000, v4
	v_or3_b32 v4, v9, v4, v6
	s_add_i32 s58, 0, 0x10000
	s_add_i32 s59, 0, 0x14000
	s_mov_b32 s53, 0x18000
	s_mov_b32 s54, 0x8000
	v_mov_b32_e32 v151, v147
	v_add_u32_e32 v152, v4, v10
	v_mov_b32_e32 v153, v147
	v_mov_b32_e32 v154, s99
	v_mov_b32_e32 v155, 0
	v_add_u32_e32 v156, -1, v154
	v_mov_b32_e32 v157, 0
	v_add_u32_e32 v162, s58, v149
	v_add_u32_e32 v163, s59, v149
	v_add_u32_e32 v164, 0, v3
	v_add_u32_e32 v165, v0, v2
	v_add_u32_e32 v166, v1, v5
	s_mov_b32 s60, 0x4c000
	s_mov_b64 s[14:15], 0xa0000
	s_mov_b32 s61, 0xa0000
	s_mov_b32 s62, 0xa8000
	s_mov_b32 s63, 0x50000
	s_mov_b32 s64, 0x54000
	s_mov_b64 s[24:25], 0xb0000
	s_mov_b32 s65, 0xb0000
	s_mov_b64 s[26:27], 0xb8000
	s_mov_b32 s66, 0xb8000
	s_mov_b32 s67, 0x58000
	s_mov_b32 s68, 0
	s_barrier
	s_branch .LBB0_768

.LBB0_768:
	s_add_i32 s68, s68, 1
	s_mul_i32 s0, s68, s55
	s_mul_hi_u32 s1, s68, s33
	s_add_i32 s1, s1, s0
	s_mul_i32 s0, s68, s33
	s_add_u32 s36, s0, s98
	s_addc_u32 s37, s1, s35
	v_cmp_gt_i64_e32 vcc, s[36:37], v[156:157]
	v_cmp_lt_i64_e64 s[0:1], s[36:37], v[154:155]
	s_cbranch_vccnz .LBB0_770
	s_ashr_i32 s28, s36, 31
	s_lshr_b32 s28, s28, 29
	s_add_i32 s28, s36, s28
	s_ashr_i32 s29, s28, 3
	s_and_b32 s28, s28, -8
	s_sub_i32 s28, s36, s28
	s_cmp_lt_i32 s28, 0
	s_cselect_b32 s30, s46, 0x50
	s_mul_i32 s28, s28, s30
	s_add_i32 s28, s28, s29
	s_ashr_i32 s29, s28, 31
	s_lshr_b32 s29, s29, 28
	s_add_i32 s29, s28, s29
	s_ashr_i32 s30, s29, 4
	s_lshl_b32 s30, s30, 2
	s_sub_i32 s31, 0xa0, s30
	s_min_i32 s31, s31, 4
	s_abs_i32 s36, s31
	v_cvt_f32_u32_e32 v0, s36
	s_sub_i32 s38, 0, s36
	s_and_b32 s29, s29, -16
	s_sub_i32 s29, s28, s29
	v_rcp_iflag_f32_e32 v0, v0
	s_abs_i32 s28, s29
	s_xor_b32 s37, s29, s31
	s_ashr_i32 s37, s37, 31
	v_mul_f32_e32 v0, 0x4f7ffffe, v0
	v_cvt_u32_f32_e32 v0, v0
	s_nop 0
	v_readfirstlane_b32 s39, v0
	s_mul_i32 s38, s38, s39
	s_mul_hi_u32 s38, s39, s38
	s_add_i32 s39, s39, s38
	s_mul_hi_u32 s38, s28, s39
	s_mul_i32 s39, s38, s36
	s_sub_i32 s28, s28, s39
	s_add_i32 s44, s38, 1
	s_sub_i32 s39, s28, s36
	s_cmp_ge_u32 s28, s36
	s_cselect_b32 s38, s44, s38
	s_cselect_b32 s28, s39, s28
	s_add_i32 s39, s38, 1
	s_cmp_ge_u32 s28, s36
	s_cselect_b32 s28, s39, s38
	s_xor_b32 s28, s28, s37
	s_sub_i32 s28, s28, s37
	s_mul_i32 s31, s28, s31
	s_sub_i32 s29, s29, s31
	s_add_i32 s30, s30, s29

.LBB0_774:
	s_lshl_b32 s29, s6, 8
	s_sub_i32 s6, s20, 32
	s_lshr_b32 s6, s6, 4
	s_cmp_lt_i32 s20, 32
	s_mulk_i32 s6, 0x1800
	s_cselect_b32 s6, 0xc000, s6
	s_cselect_b32 s42, s16, s56
	s_cselect_b32 s43, s17, s57
	s_add_i32 s6, s6, s29
	s_addk_i32 s6, 0x800
	s_lshl_b32 s6, s6, 2
	s_add_u32 s40, s78, s6
	s_addc_u32 s41, s79, 0
	v_lshlrev_b32_e32 v158, 2, v160
	s_lshl_b32 s31, s20, 20
	s_lshl_b32 s29, s29, 2
	s_add_u32 s31, s31, s29
	global_load_dwordx4 v[32:35], v158, s[40:41]
	global_load_dwordx4 v[36:39], v158, s[40:41] offset:16
	global_load_dwordx4 v[44:47], v158, s[40:41] offset:128
	global_load_dwordx4 v[40:43], v158, s[40:41] offset:144
	s_add_u32 s44, s42, s31
	s_addc_u32 s45, s43, 0
	s_lshr_b32 s31, s31, 1
	s_add_u32 s42, s76, s31
	s_addc_u32 s43, s77, 0
	v_lshlrev_b32_e32 v159, 12, v161
	v_lshl_add_u32 v159, v148, 2, v159
	v_add_u32_e32 v226, 0x8000, v159
	v_lshrrev_b32_e32 v227, 1, v159
	v_add_u32_e32 v228, 0x4000, v227
	global_load_dwordx4 v[168:171], v159, s[44:45]
	global_load_dwordx4 v[172:175], v159, s[44:45] offset:16
	global_load_dwordx4 v[176:179], v226, s[44:45]
	global_load_dwordx4 v[180:183], v226, s[44:45] offset:16
	s_add_u32 s44, s44, 0x10000
	s_addc_u32 s45, s45, 0
	global_load_dwordx4 v[184:187], v159, s[44:45]
	global_load_dwordx4 v[188:191], v159, s[44:45] offset:16
	global_load_dwordx4 v[192:195], v226, s[44:45]
	global_load_dwordx4 v[196:199], v226, s[44:45] offset:16
	s_add_u32 s44, s44, 0x10000
	s_addc_u32 s45, s45, 0
	global_load_dwordx4 v[200:203], v159, s[44:45]
	global_load_dwordx4 v[204:207], v159, s[44:45] offset:16
	global_load_dwordx4 v[218:221], v226, s[44:45]
	global_load_dwordx4 v[222:225], v226, s[44:45] offset:16
	s_waitcnt vmcnt(12)
	v_pk_mul_f32 v[140:141], v[140:141], v[32:33]
	v_pk_mul_f32 v[142:143], v[142:143], v[34:35]
	v_pk_mul_f32 v[136:137], v[136:137], v[36:37]
	v_pk_mul_f32 v[138:139], v[138:139], v[38:39]
	v_pk_mul_f32 v[132:133], v[132:133], v[44:45]
	v_pk_mul_f32 v[134:135], v[134:135], v[46:47]
	v_pk_mul_f32 v[128:129], v[128:129], v[40:41]
	v_pk_mul_f32 v[130:131], v[130:131], v[42:43]
	v_pk_mul_f32 v[124:125], v[124:125], v[32:33]
	v_pk_mul_f32 v[126:127], v[126:127], v[34:35]
	v_pk_mul_f32 v[120:121], v[120:121], v[36:37]
	v_pk_mul_f32 v[122:123], v[122:123], v[38:39]
	v_pk_mul_f32 v[116:117], v[116:117], v[44:45]
	v_pk_mul_f32 v[118:119], v[118:119], v[46:47]
	v_pk_mul_f32 v[112:113], v[112:113], v[40:41]
	v_pk_mul_f32 v[114:115], v[114:115], v[42:43]
	v_pk_mul_f32 v[108:109], v[108:109], v[32:33]
	v_pk_mul_f32 v[110:111], v[110:111], v[34:35]
	v_pk_mul_f32 v[104:105], v[104:105], v[36:37]
	v_pk_mul_f32 v[106:107], v[106:107], v[38:39]
	v_pk_mul_f32 v[100:101], v[100:101], v[44:45]
	v_pk_mul_f32 v[102:103], v[102:103], v[46:47]
	v_pk_mul_f32 v[96:97], v[96:97], v[40:41]
	v_pk_mul_f32 v[98:99], v[98:99], v[42:43]
	v_pk_mul_f32 v[92:93], v[92:93], v[32:33]
	v_pk_mul_f32 v[94:95], v[94:95], v[34:35]
	v_pk_mul_f32 v[88:89], v[88:89], v[36:37]
	v_pk_mul_f32 v[90:91], v[90:91], v[38:39]
	v_pk_mul_f32 v[84:85], v[84:85], v[44:45]
	v_pk_mul_f32 v[86:87], v[86:87], v[46:47]
	v_pk_mul_f32 v[80:81], v[80:81], v[40:41]
	v_pk_mul_f32 v[82:83], v[82:83], v[42:43]
	v_pk_mul_f32 v[76:77], v[76:77], v[32:33]
	v_pk_mul_f32 v[78:79], v[78:79], v[34:35]
	v_pk_mul_f32 v[72:73], v[72:73], v[36:37]
	v_pk_mul_f32 v[74:75], v[74:75], v[38:39]
	v_pk_mul_f32 v[68:69], v[68:69], v[44:45]
	v_pk_mul_f32 v[70:71], v[70:71], v[46:47]
	v_pk_mul_f32 v[64:65], v[64:65], v[40:41]
	v_pk_mul_f32 v[66:67], v[66:67], v[42:43]
	v_pk_mul_f32 v[60:61], v[60:61], v[32:33]
	v_pk_mul_f32 v[62:63], v[62:63], v[34:35]
	v_pk_mul_f32 v[56:57], v[56:57], v[36:37]
	v_pk_mul_f32 v[58:59], v[58:59], v[38:39]
	v_pk_mul_f32 v[52:53], v[52:53], v[44:45]
	v_pk_mul_f32 v[54:55], v[54:55], v[46:47]
	v_pk_mul_f32 v[48:49], v[48:49], v[40:41]
	v_pk_mul_f32 v[50:51], v[50:51], v[42:43]
	v_pk_mul_f32 v[28:29], v[28:29], v[32:33]
	v_pk_mul_f32 v[30:31], v[30:31], v[34:35]
	v_pk_mul_f32 v[24:25], v[24:25], v[36:37]
	v_pk_mul_f32 v[26:27], v[26:27], v[38:39]
	v_pk_mul_f32 v[20:21], v[20:21], v[44:45]
	v_pk_mul_f32 v[22:23], v[22:23], v[46:47]
	v_pk_mul_f32 v[16:17], v[16:17], v[40:41]
	v_pk_mul_f32 v[18:19], v[18:19], v[42:43]
	v_pk_mul_f32 v[12:13], v[12:13], v[32:33]
	v_pk_mul_f32 v[14:15], v[14:15], v[34:35]
	v_pk_mul_f32 v[8:9], v[8:9], v[36:37]
	v_pk_mul_f32 v[10:11], v[10:11], v[38:39]
	v_pk_mul_f32 v[4:5], v[4:5], v[44:45]
	v_pk_mul_f32 v[6:7], v[6:7], v[46:47]
	v_pk_mul_f32 v[0:1], v[0:1], v[40:41]
	v_pk_mul_f32 v[2:3], v[2:3], v[42:43]
	v_cvt_pk_bf16_f32 v140, v140, v141
	v_cvt_pk_bf16_f32 v141, v142, v143
	v_cvt_pk_bf16_f32 v142, v136, v137
	v_cvt_pk_bf16_f32 v143, v138, v139
	v_cvt_pk_bf16_f32 v132, v132, v133
	v_cvt_pk_bf16_f32 v133, v134, v135
	v_cvt_pk_bf16_f32 v134, v128, v129
	v_cvt_pk_bf16_f32 v135, v130, v131
	v_cvt_pk_bf16_f32 v124, v124, v125
	v_cvt_pk_bf16_f32 v125, v126, v127
	v_cvt_pk_bf16_f32 v126, v120, v121
	v_cvt_pk_bf16_f32 v127, v122, v123
	v_cvt_pk_bf16_f32 v116, v116, v117
	v_cvt_pk_bf16_f32 v117, v118, v119
	v_cvt_pk_bf16_f32 v118, v112, v113
	v_cvt_pk_bf16_f32 v119, v114, v115
	v_cvt_pk_bf16_f32 v108, v108, v109
	v_cvt_pk_bf16_f32 v109, v110, v111
	v_cvt_pk_bf16_f32 v110, v104, v105
	v_cvt_pk_bf16_f32 v111, v106, v107
	v_cvt_pk_bf16_f32 v100, v100, v101
	v_cvt_pk_bf16_f32 v101, v102, v103
	v_cvt_pk_bf16_f32 v102, v96, v97
	v_cvt_pk_bf16_f32 v103, v98, v99
	v_cvt_pk_bf16_f32 v92, v92, v93
	v_cvt_pk_bf16_f32 v93, v94, v95
	v_cvt_pk_bf16_f32 v94, v88, v89
	v_cvt_pk_bf16_f32 v95, v90, v91
	v_cvt_pk_bf16_f32 v84, v84, v85
	v_cvt_pk_bf16_f32 v85, v86, v87
	v_cvt_pk_bf16_f32 v86, v80, v81
	v_cvt_pk_bf16_f32 v87, v82, v83
	v_cvt_pk_bf16_f32 v76, v76, v77
	v_cvt_pk_bf16_f32 v77, v78, v79
	v_cvt_pk_bf16_f32 v78, v72, v73
	v_cvt_pk_bf16_f32 v79, v74, v75
	v_cvt_pk_bf16_f32 v68, v68, v69
	v_cvt_pk_bf16_f32 v69, v70, v71
	v_cvt_pk_bf16_f32 v70, v64, v65
	v_cvt_pk_bf16_f32 v71, v66, v67
	v_cvt_pk_bf16_f32 v60, v60, v61
	v_cvt_pk_bf16_f32 v61, v62, v63
	v_cvt_pk_bf16_f32 v62, v56, v57
	v_cvt_pk_bf16_f32 v63, v58, v59
	v_cvt_pk_bf16_f32 v52, v52, v53
	v_cvt_pk_bf16_f32 v53, v54, v55
	v_cvt_pk_bf16_f32 v54, v48, v49
	v_cvt_pk_bf16_f32 v55, v50, v51
	v_cvt_pk_bf16_f32 v28, v28, v29
	v_cvt_pk_bf16_f32 v29, v30, v31
	v_cvt_pk_bf16_f32 v30, v24, v25
	v_cvt_pk_bf16_f32 v31, v26, v27
	v_cvt_pk_bf16_f32 v20, v20, v21
	v_cvt_pk_bf16_f32 v21, v22, v23
	v_cvt_pk_bf16_f32 v22, v16, v17
	v_cvt_pk_bf16_f32 v23, v18, v19
	v_cvt_pk_bf16_f32 v12, v12, v13
	v_cvt_pk_bf16_f32 v13, v14, v15
	v_cvt_pk_bf16_f32 v14, v8, v9
	v_cvt_pk_bf16_f32 v15, v10, v11
	v_cvt_pk_bf16_f32 v4, v4, v5
	v_cvt_pk_bf16_f32 v5, v6, v7
	v_cvt_pk_bf16_f32 v6, v0, v1
	v_cvt_pk_bf16_f32 v7, v2, v3
	s_add_u32 s44, s44, 0x10000
	s_addc_u32 s45, s45, 0
	global_load_dwordx4 v[32:35], v159, s[44:45]
	global_load_dwordx4 v[36:39], v159, s[44:45] offset:16
	global_load_dwordx4 v[40:43], v226, s[44:45]
	global_load_dwordx4 v[44:47], v226, s[44:45] offset:16
	s_add_u32 s44, s44, 0x50000
	s_addc_u32 s45, s45, 0
	global_load_dwordx4 v[128:131], v159, s[44:45]
	global_load_dwordx4 v[136:139], v159, s[44:45] offset:16
	global_load_dwordx4 v[112:115], v226, s[44:45]
	global_load_dwordx4 v[120:123], v226, s[44:45] offset:16
	s_add_u32 s44, s44, 0x10000
	s_addc_u32 s45, s45, 0
	global_load_dwordx4 v[96:99], v159, s[44:45]
	global_load_dwordx4 v[104:107], v159, s[44:45] offset:16
	global_load_dwordx4 v[80:83], v226, s[44:45]
	global_load_dwordx4 v[88:91], v226, s[44:45] offset:16
	s_add_u32 s44, s44, 0x10000
	s_addc_u32 s45, s45, 0
	global_load_dwordx4 v[64:67], v159, s[44:45]
	global_load_dwordx4 v[72:75], v159, s[44:45] offset:16
	global_load_dwordx4 v[48:51], v226, s[44:45]
	global_load_dwordx4 v[56:59], v226, s[44:45] offset:16
	s_add_u32 s44, s44, 0x10000
	s_addc_u32 s45, s45, 0
	global_load_dwordx4 v[16:19], v159, s[44:45]
	global_load_dwordx4 v[24:27], v159, s[44:45] offset:16
	global_load_dwordx4 v[0:3], v226, s[44:45]
	global_load_dwordx4 v[8:11], v226, s[44:45] offset:16
	ds_write_b128 v165, v[140:143]
	ds_write_b128 v165, v[132:135] offset:64
	ds_read_b128 v[140:143], v166
	ds_read_b128 v[132:135], v166 offset:1152
	s_waitcnt vmcnt(28)
	s_waitcnt lgkmcnt(1)
	v_lshlrev_b32_e32 v230, 16, v140
	v_and_b32_e32 v231, 0xffff0000, v140
	v_pk_add_f32 v[168:169], v[168:169], v[230:231]
	v_lshlrev_b32_e32 v230, 16, v141
	v_and_b32_e32 v231, 0xffff0000, v141
	v_pk_add_f32 v[170:171], v[170:171], v[230:231]
	v_lshlrev_b32_e32 v230, 16, v142
	v_and_b32_e32 v231, 0xffff0000, v142
	v_pk_add_f32 v[172:173], v[172:173], v[230:231]
	v_lshlrev_b32_e32 v230, 16, v143
	v_and_b32_e32 v231, 0xffff0000, v143
	v_pk_add_f32 v[174:175], v[174:175], v[230:231]
	v_cvt_pk_bf16_f32 v140, v168, v169
	v_cvt_pk_bf16_f32 v141, v170, v171
	v_cvt_pk_bf16_f32 v142, v172, v173
	v_cvt_pk_bf16_f32 v143, v174, v175
	global_store_dwordx4 v227, v[140:143], s[42:43]
	s_waitcnt lgkmcnt(0)
	v_lshlrev_b32_e32 v230, 16, v132
	v_and_b32_e32 v231, 0xffff0000, v132
	v_pk_add_f32 v[176:177], v[176:177], v[230:231]
	v_lshlrev_b32_e32 v230, 16, v133
	v_and_b32_e32 v231, 0xffff0000, v133
	v_pk_add_f32 v[178:179], v[178:179], v[230:231]
	v_lshlrev_b32_e32 v230, 16, v134
	v_and_b32_e32 v231, 0xffff0000, v134
	v_pk_add_f32 v[180:181], v[180:181], v[230:231]
	v_lshlrev_b32_e32 v230, 16, v135
	v_and_b32_e32 v231, 0xffff0000, v135
	v_pk_add_f32 v[182:183], v[182:183], v[230:231]
	v_cvt_pk_bf16_f32 v132, v176, v177
	v_cvt_pk_bf16_f32 v133, v178, v179
	v_cvt_pk_bf16_f32 v134, v180, v181
	v_cvt_pk_bf16_f32 v135, v182, v183
	global_store_dwordx4 v228, v[132:135], s[42:43]
	s_add_u32 s42, s42, 0x8000
	s_addc_u32 s43, s43, 0
	ds_write_b128 v165, v[124:127]
	ds_write_b128 v165, v[116:119] offset:64
	ds_read_b128 v[124:127], v166
	ds_read_b128 v[116:119], v166 offset:1152
	s_waitcnt vmcnt(26)
	s_waitcnt lgkmcnt(1)
	v_lshlrev_b32_e32 v230, 16, v124
	v_and_b32_e32 v231, 0xffff0000, v124
	v_pk_add_f32 v[184:185], v[184:185], v[230:231]
	v_lshlrev_b32_e32 v230, 16, v125
	v_and_b32_e32 v231, 0xffff0000, v125
	v_pk_add_f32 v[186:187], v[186:187], v[230:231]
	v_lshlrev_b32_e32 v230, 16, v126
	v_and_b32_e32 v231, 0xffff0000, v126
	v_pk_add_f32 v[188:189], v[188:189], v[230:231]
	v_lshlrev_b32_e32 v230, 16, v127
	v_and_b32_e32 v231, 0xffff0000, v127
	v_pk_add_f32 v[190:191], v[190:191], v[230:231]
	v_cvt_pk_bf16_f32 v124, v184, v185
	v_cvt_pk_bf16_f32 v125, v186, v187
	v_cvt_pk_bf16_f32 v126, v188, v189
	v_cvt_pk_bf16_f32 v127, v190, v191
	global_store_dwordx4 v227, v[124:127], s[42:43]
	s_waitcnt lgkmcnt(0)
	v_lshlrev_b32_e32 v230, 16, v116
	v_and_b32_e32 v231, 0xffff0000, v116
	v_pk_add_f32 v[192:193], v[192:193], v[230:231]
	v_lshlrev_b32_e32 v230, 16, v117
	v_and_b32_e32 v231, 0xffff0000, v117
	v_pk_add_f32 v[194:195], v[194:195], v[230:231]
	v_lshlrev_b32_e32 v230, 16, v118
	v_and_b32_e32 v231, 0xffff0000, v118
	v_pk_add_f32 v[196:197], v[196:197], v[230:231]
	v_lshlrev_b32_e32 v230, 16, v119
	v_and_b32_e32 v231, 0xffff0000, v119
	v_pk_add_f32 v[198:199], v[198:199], v[230:231]
	v_cvt_pk_bf16_f32 v116, v192, v193
	v_cvt_pk_bf16_f32 v117, v194, v195
	v_cvt_pk_bf16_f32 v118, v196, v197
	v_cvt_pk_bf16_f32 v119, v198, v199
	global_store_dwordx4 v228, v[116:119], s[42:43]
	s_add_u32 s42, s42, 0x8000
	s_addc_u32 s43, s43, 0
	ds_write_b128 v165, v[108:111]
	ds_write_b128 v165, v[100:103] offset:64
	ds_read_b128 v[108:111], v166
	ds_read_b128 v[100:103], v166 offset:1152
	s_waitcnt vmcnt(24)
	s_waitcnt lgkmcnt(1)
	v_lshlrev_b32_e32 v230, 16, v108
	v_and_b32_e32 v231, 0xffff0000, v108
	v_pk_add_f32 v[200:201], v[200:201], v[230:231]
	v_lshlrev_b32_e32 v230, 16, v109
	v_and_b32_e32 v231, 0xffff0000, v109
	v_pk_add_f32 v[202:203], v[202:203], v[230:231]
	v_lshlrev_b32_e32 v230, 16, v110
	v_and_b32_e32 v231, 0xffff0000, v110
	v_pk_add_f32 v[204:205], v[204:205], v[230:231]
	v_lshlrev_b32_e32 v230, 16, v111
	v_and_b32_e32 v231, 0xffff0000, v111
	v_pk_add_f32 v[206:207], v[206:207], v[230:231]
	v_cvt_pk_bf16_f32 v108, v200, v201
	v_cvt_pk_bf16_f32 v109, v202, v203
	v_cvt_pk_bf16_f32 v110, v204, v205
	v_cvt_pk_bf16_f32 v111, v206, v207
	global_store_dwordx4 v227, v[108:111], s[42:43]
	s_waitcnt lgkmcnt(0)
	v_lshlrev_b32_e32 v230, 16, v100
	v_and_b32_e32 v231, 0xffff0000, v100
	v_pk_add_f32 v[218:219], v[218:219], v[230:231]
	v_lshlrev_b32_e32 v230, 16, v101
	v_and_b32_e32 v231, 0xffff0000, v101
	v_pk_add_f32 v[220:221], v[220:221], v[230:231]
	v_lshlrev_b32_e32 v230, 16, v102
	v_and_b32_e32 v231, 0xffff0000, v102
	v_pk_add_f32 v[222:223], v[222:223], v[230:231]
	v_lshlrev_b32_e32 v230, 16, v103
	v_and_b32_e32 v231, 0xffff0000, v103
	v_pk_add_f32 v[224:225], v[224:225], v[230:231]
	v_cvt_pk_bf16_f32 v100, v218, v219
	v_cvt_pk_bf16_f32 v101, v220, v221
	v_cvt_pk_bf16_f32 v102, v222, v223
	v_cvt_pk_bf16_f32 v103, v224, v225
	global_store_dwordx4 v228, v[100:103], s[42:43]
	s_add_u32 s42, s42, 0x8000
	s_addc_u32 s43, s43, 0
	ds_write_b128 v165, v[92:95]
	ds_write_b128 v165, v[84:87] offset:64
	ds_read_b128 v[92:95], v166
	ds_read_b128 v[84:87], v166 offset:1152
	s_waitcnt vmcnt(22)
	s_waitcnt lgkmcnt(1)
	v_lshlrev_b32_e32 v230, 16, v92
	v_and_b32_e32 v231, 0xffff0000, v92
	v_pk_add_f32 v[32:33], v[32:33], v[230:231]
	v_lshlrev_b32_e32 v230, 16, v93
	v_and_b32_e32 v231, 0xffff0000, v93
	v_pk_add_f32 v[34:35], v[34:35], v[230:231]
	v_lshlrev_b32_e32 v230, 16, v94
	v_and_b32_e32 v231, 0xffff0000, v94
	v_pk_add_f32 v[36:37], v[36:37], v[230:231]
	v_lshlrev_b32_e32 v230, 16, v95
	v_and_b32_e32 v231, 0xffff0000, v95
	v_pk_add_f32 v[38:39], v[38:39], v[230:231]
	v_cvt_pk_bf16_f32 v92, v32, v33
	v_cvt_pk_bf16_f32 v93, v34, v35
	v_cvt_pk_bf16_f32 v94, v36, v37
	v_cvt_pk_bf16_f32 v95, v38, v39
	global_store_dwordx4 v227, v[92:95], s[42:43]
	s_waitcnt lgkmcnt(0)
	v_lshlrev_b32_e32 v230, 16, v84
	v_and_b32_e32 v231, 0xffff0000, v84
	v_pk_add_f32 v[40:41], v[40:41], v[230:231]
	v_lshlrev_b32_e32 v230, 16, v85
	v_and_b32_e32 v231, 0xffff0000, v85
	v_pk_add_f32 v[42:43], v[42:43], v[230:231]
	v_lshlrev_b32_e32 v230, 16, v86
	v_and_b32_e32 v231, 0xffff0000, v86
	v_pk_add_f32 v[44:45], v[44:45], v[230:231]
	v_lshlrev_b32_e32 v230, 16, v87
	v_and_b32_e32 v231, 0xffff0000, v87
	v_pk_add_f32 v[46:47], v[46:47], v[230:231]
	v_cvt_pk_bf16_f32 v84, v40, v41
	v_cvt_pk_bf16_f32 v85, v42, v43
	v_cvt_pk_bf16_f32 v86, v44, v45
	v_cvt_pk_bf16_f32 v87, v46, v47
	global_store_dwordx4 v228, v[84:87], s[42:43]
	s_add_u32 s42, s42, 0x28000
	s_addc_u32 s43, s43, 0
	ds_write_b128 v165, v[76:79]
	ds_write_b128 v165, v[68:71] offset:64
	ds_read_b128 v[76:79], v166
	ds_read_b128 v[68:71], v166 offset:1152
	s_waitcnt vmcnt(20)
	s_waitcnt lgkmcnt(1)
	v_lshlrev_b32_e32 v230, 16, v76
	v_and_b32_e32 v231, 0xffff0000, v76
	v_pk_add_f32 v[128:129], v[128:129], v[230:231]
	v_lshlrev_b32_e32 v230, 16, v77
	v_and_b32_e32 v231, 0xffff0000, v77
	v_pk_add_f32 v[130:131], v[130:131], v[230:231]
	v_lshlrev_b32_e32 v230, 16, v78
	v_and_b32_e32 v231, 0xffff0000, v78
	v_pk_add_f32 v[136:137], v[136:137], v[230:231]
	v_lshlrev_b32_e32 v230, 16, v79
	v_and_b32_e32 v231, 0xffff0000, v79
	v_pk_add_f32 v[138:139], v[138:139], v[230:231]
	v_cvt_pk_bf16_f32 v76, v128, v129
	v_cvt_pk_bf16_f32 v77, v130, v131
	v_cvt_pk_bf16_f32 v78, v136, v137
	v_cvt_pk_bf16_f32 v79, v138, v139
	global_store_dwordx4 v227, v[76:79], s[42:43]
	s_waitcnt lgkmcnt(0)
	v_lshlrev_b32_e32 v230, 16, v68
	v_and_b32_e32 v231, 0xffff0000, v68
	v_pk_add_f32 v[112:113], v[112:113], v[230:231]
	v_lshlrev_b32_e32 v230, 16, v69
	v_and_b32_e32 v231, 0xffff0000, v69
	v_pk_add_f32 v[114:115], v[114:115], v[230:231]
	v_lshlrev_b32_e32 v230, 16, v70
	v_and_b32_e32 v231, 0xffff0000, v70
	v_pk_add_f32 v[120:121], v[120:121], v[230:231]
	v_lshlrev_b32_e32 v230, 16, v71
	v_and_b32_e32 v231, 0xffff0000, v71
	v_pk_add_f32 v[122:123], v[122:123], v[230:231]
	v_cvt_pk_bf16_f32 v68, v112, v113
	v_cvt_pk_bf16_f32 v69, v114, v115
	v_cvt_pk_bf16_f32 v70, v120, v121
	v_cvt_pk_bf16_f32 v71, v122, v123
	global_store_dwordx4 v228, v[68:71], s[42:43]
	s_add_u32 s42, s42, 0x8000
	s_addc_u32 s43, s43, 0
	ds_write_b128 v165, v[60:63]
	ds_write_b128 v165, v[52:55] offset:64
	ds_read_b128 v[60:63], v166
	ds_read_b128 v[52:55], v166 offset:1152
	s_waitcnt vmcnt(18)
	s_waitcnt lgkmcnt(1)
	v_lshlrev_b32_e32 v230, 16, v60
	v_and_b32_e32 v231, 0xffff0000, v60
	v_pk_add_f32 v[96:97], v[96:97], v[230:231]
	v_lshlrev_b32_e32 v230, 16, v61
	v_and_b32_e32 v231, 0xffff0000, v61
	v_pk_add_f32 v[98:99], v[98:99], v[230:231]
	v_lshlrev_b32_e32 v230, 16, v62
	v_and_b32_e32 v231, 0xffff0000, v62
	v_pk_add_f32 v[104:105], v[104:105], v[230:231]
	v_lshlrev_b32_e32 v230, 16, v63
	v_and_b32_e32 v231, 0xffff0000, v63
	v_pk_add_f32 v[106:107], v[106:107], v[230:231]
	v_cvt_pk_bf16_f32 v60, v96, v97
	v_cvt_pk_bf16_f32 v61, v98, v99
	v_cvt_pk_bf16_f32 v62, v104, v105
	v_cvt_pk_bf16_f32 v63, v106, v107
	global_store_dwordx4 v227, v[60:63], s[42:43]
	s_waitcnt lgkmcnt(0)
	v_lshlrev_b32_e32 v230, 16, v52
	v_and_b32_e32 v231, 0xffff0000, v52
	v_pk_add_f32 v[80:81], v[80:81], v[230:231]
	v_lshlrev_b32_e32 v230, 16, v53
	v_and_b32_e32 v231, 0xffff0000, v53
	v_pk_add_f32 v[82:83], v[82:83], v[230:231]
	v_lshlrev_b32_e32 v230, 16, v54
	v_and_b32_e32 v231, 0xffff0000, v54
	v_pk_add_f32 v[88:89], v[88:89], v[230:231]
	v_lshlrev_b32_e32 v230, 16, v55
	v_and_b32_e32 v231, 0xffff0000, v55
	v_pk_add_f32 v[90:91], v[90:91], v[230:231]
	v_cvt_pk_bf16_f32 v52, v80, v81
	v_cvt_pk_bf16_f32 v53, v82, v83
	v_cvt_pk_bf16_f32 v54, v88, v89
	v_cvt_pk_bf16_f32 v55, v90, v91
	global_store_dwordx4 v228, v[52:55], s[42:43]
	s_add_u32 s42, s42, 0x8000
	s_addc_u32 s43, s43, 0
	ds_write_b128 v165, v[28:31]
	ds_write_b128 v165, v[20:23] offset:64
	ds_read_b128 v[28:31], v166
	ds_read_b128 v[20:23], v166 offset:1152
	s_waitcnt vmcnt(16)
	s_waitcnt lgkmcnt(1)
	v_lshlrev_b32_e32 v230, 16, v28
	v_and_b32_e32 v231, 0xffff0000, v28
	v_pk_add_f32 v[64:65], v[64:65], v[230:231]
	v_lshlrev_b32_e32 v230, 16, v29
	v_and_b32_e32 v231, 0xffff0000, v29
	v_pk_add_f32 v[66:67], v[66:67], v[230:231]
	v_lshlrev_b32_e32 v230, 16, v30
	v_and_b32_e32 v231, 0xffff0000, v30
	v_pk_add_f32 v[72:73], v[72:73], v[230:231]
	v_lshlrev_b32_e32 v230, 16, v31
	v_and_b32_e32 v231, 0xffff0000, v31
	v_pk_add_f32 v[74:75], v[74:75], v[230:231]
	v_cvt_pk_bf16_f32 v28, v64, v65
	v_cvt_pk_bf16_f32 v29, v66, v67
	v_cvt_pk_bf16_f32 v30, v72, v73
	v_cvt_pk_bf16_f32 v31, v74, v75
	global_store_dwordx4 v227, v[28:31], s[42:43]
	s_waitcnt lgkmcnt(0)
	v_lshlrev_b32_e32 v230, 16, v20
	v_and_b32_e32 v231, 0xffff0000, v20
	v_pk_add_f32 v[48:49], v[48:49], v[230:231]
	v_lshlrev_b32_e32 v230, 16, v21
	v_and_b32_e32 v231, 0xffff0000, v21
	v_pk_add_f32 v[50:51], v[50:51], v[230:231]
	v_lshlrev_b32_e32 v230, 16, v22
	v_and_b32_e32 v231, 0xffff0000, v22
	v_pk_add_f32 v[56:57], v[56:57], v[230:231]
	v_lshlrev_b32_e32 v230, 16, v23
	v_and_b32_e32 v231, 0xffff0000, v23
	v_pk_add_f32 v[58:59], v[58:59], v[230:231]
	v_cvt_pk_bf16_f32 v20, v48, v49
	v_cvt_pk_bf16_f32 v21, v50, v51
	v_cvt_pk_bf16_f32 v22, v56, v57
	v_cvt_pk_bf16_f32 v23, v58, v59
	global_store_dwordx4 v228, v[20:23], s[42:43]
	s_add_u32 s42, s42, 0x8000
	s_addc_u32 s43, s43, 0
	ds_write_b128 v165, v[12:15]
	ds_write_b128 v165, v[4:7] offset:64
	ds_read_b128 v[12:15], v166
	ds_read_b128 v[4:7], v166 offset:1152
	s_waitcnt vmcnt(14)
	s_waitcnt lgkmcnt(1)
	v_lshlrev_b32_e32 v230, 16, v12
	v_and_b32_e32 v231, 0xffff0000, v12
	v_pk_add_f32 v[16:17], v[16:17], v[230:231]
	v_lshlrev_b32_e32 v230, 16, v13
	v_and_b32_e32 v231, 0xffff0000, v13
	v_pk_add_f32 v[18:19], v[18:19], v[230:231]
	v_lshlrev_b32_e32 v230, 16, v14
	v_and_b32_e32 v231, 0xffff0000, v14
	v_pk_add_f32 v[24:25], v[24:25], v[230:231]
	v_lshlrev_b32_e32 v230, 16, v15
	v_and_b32_e32 v231, 0xffff0000, v15
	v_pk_add_f32 v[26:27], v[26:27], v[230:231]
	v_cvt_pk_bf16_f32 v12, v16, v17
	v_cvt_pk_bf16_f32 v13, v18, v19
	v_cvt_pk_bf16_f32 v14, v24, v25
	v_cvt_pk_bf16_f32 v15, v26, v27
	global_store_dwordx4 v227, v[12:15], s[42:43]
	s_waitcnt lgkmcnt(0)
	v_lshlrev_b32_e32 v230, 16, v4
	v_and_b32_e32 v231, 0xffff0000, v4
	v_pk_add_f32 v[0:1], v[0:1], v[230:231]
	v_lshlrev_b32_e32 v230, 16, v5
	v_and_b32_e32 v231, 0xffff0000, v5
	v_pk_add_f32 v[2:3], v[2:3], v[230:231]
	v_lshlrev_b32_e32 v230, 16, v6
	v_and_b32_e32 v231, 0xffff0000, v6
	v_pk_add_f32 v[8:9], v[8:9], v[230:231]
	v_lshlrev_b32_e32 v230, 16, v7
	v_and_b32_e32 v231, 0xffff0000, v7
	v_pk_add_f32 v[10:11], v[10:11], v[230:231]
	v_cvt_pk_bf16_f32 v4, v0, v1
	v_cvt_pk_bf16_f32 v5, v2, v3
	v_cvt_pk_bf16_f32 v6, v8, v9
	v_cvt_pk_bf16_f32 v7, v10, v11
	global_store_dwordx4 v228, v[4:7], s[42:43]
	s_andn2_b64 vcc, exec, s[0:1]
	s_mov_b64 s[0:1], -1
	s_cbranch_vccnz .LBB0_767
	s_andn2_b64 vcc, exec, s[8:9]
	s_cbranch_vccnz .LBB0_766
	s_barrier
	s_branch .LBB0_766

.LBB0_778:
	s_cmp_eq_u32 s100, 1
	s_cbranch_scc1 .Lseam5_body
	s_cmp_gt_i32 s83, 7
	s_cselect_b64 s[0:1], -1, 0
	s_and_b64 s[4:5], s[4:5], s[0:1]
	v_readlane_b32 s74, v254, 48
	v_readlane_b32 s70, v254, 46
	v_readlane_b32 s84, v254, 50
	s_andn2_b64 vcc, exec, s[4:5]
	v_readlane_b32 s75, v254, 49
	v_readlane_b32 s71, v254, 47
	v_readlane_b32 s85, v254, 51
	s_cbranch_vccnz .LBB0_828
	s_waitcnt vmcnt(0)
	v_cmp_eq_u32_e32 vcc, 0, v210
	s_waitcnt vmcnt(0) lgkmcnt(0)
	s_barrier
	s_and_saveexec_b64 s[4:5], vcc
	s_cbranch_execz .LBB0_827
	s_add_i32 s3, 0, 0x20200
	v_mov_b32_e32 v0, s3
	s_waitcnt vmcnt(0) expcnt(0) lgkmcnt(0)
	ds_read_b32 v2, v0
	s_add_i32 s3, 0, 0x20204
	v_mov_b32_e32 v0, s3
	ds_read_b32 v0, v0
	s_waitcnt lgkmcnt(1)
	v_cmp_ne_u32_e32 vcc, 0, v2
	s_cbranch_vccnz .LBB0_795
	v_readlane_b32 s6, v254, 8
	v_readlane_b32 s7, v254, 9
	s_load_dwordx2 s[10:11], s[6:7], 0x4
	s_add_u32 s6, s78, 0x1e00200
	s_addc_u32 s7, s79, 0
	s_add_u32 s8, s78, 0x1e00400
	s_addc_u32 s9, s79, 0
	s_waitcnt lgkmcnt(0)
	s_mul_i32 s3, s10, s33
	s_add_u32 s10, s78, 0x1e00500
	s_mul_i32 s3, s3, s11
	s_addc_u32 s11, s79, 0
	s_add_u32 s12, s78, 0x1e00600
	s_addc_u32 s13, s79, 0
	s_add_u32 s14, s78, 0x1e00700
	s_addc_u32 s15, s79, 0
	s_add_u32 s16, s78, 0x1e00800
	s_addc_u32 s17, s79, 0
	s_add_u32 s18, s78, 0x1e00900
	s_addc_u32 s19, s79, 0
	s_add_u32 s20, s78, 0x1e00a00
	s_addc_u32 s21, s79, 0
	s_add_u32 s24, s78, 0x1e00b00
	s_addc_u32 s25, s79, 0
	s_add_u32 s26, s78, 0x1e00c00
	s_addc_u32 s27, s79, 0
	s_add_u32 s28, s78, 0x1e00d00
	s_addc_u32 s29, s79, 0
	s_add_u32 s30, s78, 0x1e00e00
	s_addc_u32 s31, s79, 0
	s_add_u32 s36, s78, 0x1e00f00
	s_addc_u32 s37, s79, 0
	s_add_u32 s38, s78, 0x1e01000
	s_addc_u32 s39, s79, 0
	s_add_u32 s40, s78, 0x1e01100
	s_addc_u32 s41, s79, 0
	s_add_u32 s42, s78, 0x1e01200
	s_addc_u32 s43, s79, 0
	s_add_u32 s44, s78, 0x1e01300
	s_addc_u32 s45, s79, 0
	s_mov_b32 s35, 1
	v_mov_b32_e32 v16, 0
	s_branch .LBB0_783
